# norm loop simplified: per-wave direct loads of its batch's shift/scale vectors (contiguous rows per wave), no LDS parameter table and no workgroup barriers
# speedup vs baseline: 1.0058x; 1.0058x over previous
; __device__ __forceinline__ f32x4 bf4_to_f32(u32x2 w) { return (f32x4){__builtin_bit_cast(float, w.x << 16), __builtin_bit_cast(float, w.x & 0xffff0000u), __builtin_bit_cast(float, w.y << 16), __builtin_bit_cast(float, w.y & 0xffff0000u)}; }
; __device__ __forceinline__ void norm_phase(const Params& P, unsigned char* ws, int layer, int which, int nrows, bool first, int lane, int wave, const float* pend_part, int pend_ns, const float* pend_gate) {
;     ...
;     for (int row0 = gw; row0 < MLAT; row0 += NR * NGW) {
;         f32x4 v[NR][2][2]; float ss[NR];
; #pragma unroll
;         for (int r = 0; r < NR; ++r) { const int row = row0 + r * NGW; ss[r] = 0.f;
; #pragma unroll
;             for (int j = 0; j < 2; ++j) { const int col = 8 * lane + 512 * j;
;                 if (first) { v[r][j][0] = *(const f32x4*)(P.in[I_X] + (size_t)row * DM + col); v[r][j][1] = *(const f32x4*)(P.in[I_X] + (size_t)row * DM + col + 4); }
;                 else { const u32x4 w = *(const u32x4*)(XB + (size_t)row * DM + col); v[r][j][0] = bf4_to_f32((u32x2){w.x, w.y}); v[r][j][1] = bf4_to_f32((u32x2){w.z, w.w}); } } }
; #pragma unroll
;         for (int r = 0; r < NR; ++r)
; #pragma unroll
;             for (int j = 0; j < 2; ++j)
; #pragma unroll
;                 for (int q = 0; q < 2; ++q) ss[r] += (v[r][j][q][0] * v[r][j][q][0] + v[r][j][q][1] * v[r][j][q][1]) + (v[r][j][q][2] * v[r][j][q][2] + v[r][j][q][3] * v[r][j][q][3]);
; #pragma unroll
;         for (int r = 0; r < NR; ++r) { const int row = row0 + r * NGW;
;             const float rstd = rsqrtf(wave_sum(ss[r], lane) * (1.0f / DM) + EPS);
;             const float* mod = (const float*)(ws + WS_MOD) + (size_t)(layer * 9 + (row >> 12)) * 6144 + which * 3 * DM;
; #pragma unroll
;             for (int j = 0; j < 2; ++j) { const int col = 8 * lane + 512 * j; u32x4 hw, xw;
; #pragma unroll
;                 for (int q = 0; q < 2; ++q) {
;                     const f32x4 g4 = *(const f32x4*)(g + col + 4 * q), sh = *(const f32x4*)(mod + col + 4 * q), sc = *(const f32x4*)(mod + DM + col + 4 * q);
.Lmy_norm_entry:
	s_waitcnt vmcnt(0) lgkmcnt(0)
	v_readlane_b32 s48, v251, 10
	v_readlane_b32 s49, v251, 11
	v_readlane_b32 s50, v251, 12
	v_readlane_b32 s51, v251, 13
	v_readlane_b32 s52, v251, 14
	v_readlane_b32 s53, v251, 15
	v_readlane_b32 s54, v251, 16
	v_readlane_b32 s55, v251, 17
	v_readlane_b32 s56, v251, 18
	v_readlane_b32 s57, v251, 19
	v_readlane_b32 s58, v251, 20
	v_readlane_b32 s59, v251, 21
	v_readlane_b32 s60, v251, 22
	v_readlane_b32 s61, v251, 23
	v_readlane_b32 s62, v251, 24
	v_readlane_b32 s63, v251, 25
	s_add_u32 s22, s62, 0x4000000
	s_addc_u32 s23, s63, 0
	s_add_u32 s26, s20, 0x6400000
	s_addc_u32 s27, s21, 0
	v_lshlrev_b32_e32 v2, 4, v221
	v_lshlrev_b32_e32 v3, 5, v221
	v_lshlrev_b32_e32 v0, 2, v221
	s_lshl_b32 s98, s2, 4
	s_lshr_b32 s10, s2, 8
	s_lshl_b32 s10, s10, 12
	v_add_u32_e32 v15, s10, v3
	v_xor_b32_e32 v5, 4, v0
	v_xor_b32_e32 v6, 8, v0
	v_xor_b32_e32 v7, 16, v0
	v_xor_b32_e32 v9, 32, v0
	v_xor_b32_e32 v10, 64, v0
	v_xor_b32_e32 v11, 0x80, v0
	s_lshr_b32 s10, s2, 8
	s_add_i32 s10, s10, s12
	s_mul_hi_i32 s13, s10, 0x6000
	s_mulk_i32 s10, 0x6000
	s_add_u32 s0, s8, s10
	s_addc_u32 s1, s9, s13
	s_add_u32 s30, s0, 0x1000
	s_addc_u32 s31, s1, 0
	global_load_dwordx4 v[32:35], v3, s[0:1]
	global_load_dwordx4 v[36:39], v3, s[0:1] offset:16
	global_load_dwordx4 v[40:43], v3, s[0:1] offset:2048
	global_load_dwordx4 v[44:47], v3, s[0:1] offset:2064
	global_load_dwordx4 v[48:51], v3, s[30:31]
	global_load_dwordx4 v[52:55], v3, s[30:31] offset:16
	global_load_dwordx4 v[56:59], v3, s[30:31] offset:2048
	global_load_dwordx4 v[60:63], v3, s[30:31] offset:2064
	global_load_dwordx4 v[16:19], v3, s[24:25]
	global_load_dwordx4 v[20:23], v3, s[24:25] offset:16
	global_load_dwordx4 v[24:27], v3, s[24:25] offset:2048
	global_load_dwordx4 v[28:31], v3, s[24:25] offset:2064
	s_mov_b32 s10, s98
	s_lshl_b32 s10, s10, 11
	s_add_u32 s28, s22, s10
	s_addc_u32 s29, s23, 0
	global_load_dwordx4 v[64:67], v2, s[28:29]
	global_load_dwordx4 v[68:71], v2, s[28:29] offset:1024
	s_add_i32 s10, s98, 0x1
	s_lshl_b32 s10, s10, 11
	s_add_u32 s28, s22, s10
	s_addc_u32 s29, s23, 0
	global_load_dwordx4 v[72:75], v2, s[28:29]
	global_load_dwordx4 v[76:79], v2, s[28:29] offset:1024
	s_add_i32 s10, s98, 0x2
	s_lshl_b32 s10, s10, 11
	s_add_u32 s28, s22, s10
	s_addc_u32 s29, s23, 0
	global_load_dwordx4 v[80:83], v2, s[28:29]
	global_load_dwordx4 v[84:87], v2, s[28:29] offset:1024
	s_add_i32 s10, s98, 0x3
	s_lshl_b32 s10, s10, 11
	s_add_u32 s28, s22, s10
	s_addc_u32 s29, s23, 0
	global_load_dwordx4 v[88:91], v2, s[28:29]
	global_load_dwordx4 v[92:95], v2, s[28:29] offset:1024
	s_add_i32 s10, s98, 0x4
	s_lshl_b32 s10, s10, 11
	s_add_u32 s28, s22, s10
	s_addc_u32 s29, s23, 0
	global_load_dwordx4 v[96:99], v2, s[28:29]
	global_load_dwordx4 v[100:103], v2, s[28:29] offset:1024
	s_add_i32 s10, s98, 0x5
	s_lshl_b32 s10, s10, 11
	s_add_u32 s28, s22, s10
	s_addc_u32 s29, s23, 0
	global_load_dwordx4 v[104:107], v2, s[28:29]
	global_load_dwordx4 v[108:111], v2, s[28:29] offset:1024
	s_add_i32 s10, s98, 0x6
	s_lshl_b32 s10, s10, 11
	s_add_u32 s28, s22, s10
	s_addc_u32 s29, s23, 0
	global_load_dwordx4 v[112:115], v2, s[28:29]
	global_load_dwordx4 v[116:119], v2, s[28:29] offset:1024
	s_add_i32 s10, s98, 0x7
	s_lshl_b32 s10, s10, 11
	s_add_u32 s28, s22, s10
	s_addc_u32 s29, s23, 0
	global_load_dwordx4 v[120:123], v2, s[28:29]
	global_load_dwordx4 v[124:127], v2, s[28:29] offset:1024
	s_waitcnt vmcnt(12)
	v_lshlrev_b32_e32 v128, 16, v64
	v_and_b32_e32 v129, 0xffff0000, v64
	v_lshlrev_b32_e32 v130, 16, v65
	v_and_b32_e32 v131, 0xffff0000, v65
	v_lshlrev_b32_e32 v132, 16, v66
	v_and_b32_e32 v133, 0xffff0000, v66
	v_lshlrev_b32_e32 v134, 16, v67
	v_and_b32_e32 v135, 0xffff0000, v67
	v_lshlrev_b32_e32 v136, 16, v68
	v_and_b32_e32 v137, 0xffff0000, v68
	v_lshlrev_b32_e32 v138, 16, v69
	v_and_b32_e32 v139, 0xffff0000, v69
	v_lshlrev_b32_e32 v140, 16, v70
	v_and_b32_e32 v141, 0xffff0000, v70
	v_lshlrev_b32_e32 v142, 16, v71
	v_and_b32_e32 v143, 0xffff0000, v71
	v_lshlrev_b32_e32 v144, 16, v72
	v_and_b32_e32 v145, 0xffff0000, v72
	v_lshlrev_b32_e32 v146, 16, v73
	v_and_b32_e32 v147, 0xffff0000, v73
	v_lshlrev_b32_e32 v148, 16, v74
	v_and_b32_e32 v149, 0xffff0000, v74
	v_lshlrev_b32_e32 v150, 16, v75
	v_and_b32_e32 v151, 0xffff0000, v75
	v_lshlrev_b32_e32 v152, 16, v76
	v_and_b32_e32 v153, 0xffff0000, v76
	v_lshlrev_b32_e32 v154, 16, v77
	v_and_b32_e32 v155, 0xffff0000, v77
	v_lshlrev_b32_e32 v156, 16, v78
	v_and_b32_e32 v157, 0xffff0000, v78
	v_lshlrev_b32_e32 v158, 16, v79
	v_and_b32_e32 v159, 0xffff0000, v79
	v_pk_mul_f32 v[160:161], v[128:129], v[128:129]
	v_pk_mul_f32 v[162:163], v[144:145], v[144:145]
	v_pk_fma_f32 v[160:161], v[130:131], v[130:131], v[160:161]
	v_pk_fma_f32 v[162:163], v[146:147], v[146:147], v[162:163]
	v_pk_fma_f32 v[160:161], v[132:133], v[132:133], v[160:161]
	v_pk_fma_f32 v[162:163], v[148:149], v[148:149], v[162:163]
	v_pk_fma_f32 v[160:161], v[134:135], v[134:135], v[160:161]
	v_pk_fma_f32 v[162:163], v[150:151], v[150:151], v[162:163]
	v_pk_fma_f32 v[160:161], v[136:137], v[136:137], v[160:161]
	v_pk_fma_f32 v[162:163], v[152:153], v[152:153], v[162:163]
	v_pk_fma_f32 v[160:161], v[138:139], v[138:139], v[160:161]
	v_pk_fma_f32 v[162:163], v[154:155], v[154:155], v[162:163]
	v_pk_fma_f32 v[160:161], v[140:141], v[140:141], v[160:161]
	v_pk_fma_f32 v[162:163], v[156:157], v[156:157], v[162:163]
	v_pk_fma_f32 v[160:161], v[142:143], v[142:143], v[160:161]
	v_pk_fma_f32 v[162:163], v[158:159], v[158:159], v[162:163]
	v_add_f32_e32 v160, v160, v161
	v_add_f32_e32 v162, v162, v163
	ds_bpermute_b32 v164, v5, v160
	ds_bpermute_b32 v165, v5, v162
	s_waitcnt lgkmcnt(0)
; __device__ __forceinline__ unsigned cvt_pk_bf16(float lo, float hi) { unsigned r; asm volatile("v_cvt_pk_bf16_f32 %0, %1, %2" : "=v"(r) : "v"(lo), "v"(hi)); return r; }
; __device__ __forceinline__ void norm_phase(const Params& P, unsigned char* ws, int layer, int which, int nrows, bool first, int lane, int wave, const float* pend_part, int pend_ns, const float* pend_gate) {
;     ...
; #pragma unroll
;         for (int r = 0; r < NR; ++r) { const int row = row0 + r * NGW;
;             const float rstd = rsqrtf(wave_sum(ss[r], lane) * (1.0f / DM) + EPS);
;             const float* mod = (const float*)(ws + WS_MOD) + (size_t)(layer * 9 + (row >> 12)) * 6144 + which * 3 * DM;
; #pragma unroll
;             for (int j = 0; j < 2; ++j) { const int col = 8 * lane + 512 * j; u32x4 hw, xw;
; #pragma unroll
;                 for (int q = 0; q < 2; ++q) {
;                     const f32x4 g4 = *(const f32x4*)(g + col + 4 * q), sh = *(const f32x4*)(mod + col + 4 * q), sc = *(const f32x4*)(mod + DM + col + 4 * q);
;                     const f32x4 h = (v[r][j][q] * rstd) * g4 * (sc + 1.0f) + sh;
;                     if (q == 0) { hw.x = cvt_pk_bf16(h[0], h[1]); hw.y = cvt_pk_bf16(h[2], h[3]); xw.x = cvt_pk_bf16(v[r][j][q][0], v[r][j][q][1]); xw.y = cvt_pk_bf16(v[r][j][q][2], v[r][j][q][3]); }
;                     else { hw.z = cvt_pk_bf16(h[0], h[1]); hw.w = cvt_pk_bf16(h[2], h[3]); xw.z = cvt_pk_bf16(v[r][j][q][0], v[r][j][q][1]); xw.w = cvt_pk_bf16(v[r][j][q][2], v[r][j][q][3]); }
;                 }
;                 *(u32x4*)(H + (size_t)row * DM + col) = hw;
;                 if (first) *(u32x4*)(XB + (size_t)row * DM + col) = xw;
;             } }
	v_add_f32_e32 v160, v160, v164
	v_add_f32_e32 v162, v162, v165
	ds_bpermute_b32 v164, v6, v160
	ds_bpermute_b32 v165, v6, v162
	s_waitcnt lgkmcnt(0)
	v_add_f32_e32 v160, v160, v164
	v_add_f32_e32 v162, v162, v165
	ds_bpermute_b32 v164, v7, v160
	ds_bpermute_b32 v165, v7, v162
	s_waitcnt lgkmcnt(0)
	v_add_f32_e32 v160, v160, v164
	v_add_f32_e32 v162, v162, v165
	ds_bpermute_b32 v164, v9, v160
	ds_bpermute_b32 v165, v9, v162
	s_waitcnt lgkmcnt(0)
	v_add_f32_e32 v160, v160, v164
	v_add_f32_e32 v162, v162, v165
	ds_bpermute_b32 v164, v10, v160
	ds_bpermute_b32 v165, v10, v162
	s_waitcnt lgkmcnt(0)
	v_add_f32_e32 v160, v160, v164
	v_add_f32_e32 v162, v162, v165
	ds_bpermute_b32 v164, v11, v160
	ds_bpermute_b32 v165, v11, v162
	s_waitcnt lgkmcnt(0)
	v_add_f32_e32 v160, v160, v164
	v_add_f32_e32 v162, v162, v165
	v_fmamk_f32 v160, v160, 0x3a800000, v194
	v_fmamk_f32 v162, v162, 0x3a800000, v194
	v_rsq_f32_e32 v160, v160
	v_rsq_f32_e32 v162, v162
	v_pk_add_f32 v[48:49], v[48:49], 1.0 op_sel_hi:[1,0]
	v_pk_add_f32 v[50:51], v[50:51], 1.0 op_sel_hi:[1,0]
	v_pk_add_f32 v[52:53], v[52:53], 1.0 op_sel_hi:[1,0]
	v_pk_add_f32 v[54:55], v[54:55], 1.0 op_sel_hi:[1,0]
	v_pk_add_f32 v[56:57], v[56:57], 1.0 op_sel_hi:[1,0]
	v_pk_add_f32 v[58:59], v[58:59], 1.0 op_sel_hi:[1,0]
	v_pk_add_f32 v[60:61], v[60:61], 1.0 op_sel_hi:[1,0]
	v_pk_add_f32 v[62:63], v[62:63], 1.0 op_sel_hi:[1,0]
	v_pk_mul_f32 v[128:129], v[160:161], v[128:129] op_sel_hi:[0,1]
	v_pk_mul_f32 v[130:131], v[160:161], v[130:131] op_sel_hi:[0,1]
	v_pk_mul_f32 v[132:133], v[160:161], v[132:133] op_sel_hi:[0,1]
	v_pk_mul_f32 v[134:135], v[160:161], v[134:135] op_sel_hi:[0,1]
	v_pk_mul_f32 v[136:137], v[160:161], v[136:137] op_sel_hi:[0,1]
	v_pk_mul_f32 v[138:139], v[160:161], v[138:139] op_sel_hi:[0,1]
	v_pk_mul_f32 v[140:141], v[160:161], v[140:141] op_sel_hi:[0,1]
	v_pk_mul_f32 v[142:143], v[160:161], v[142:143] op_sel_hi:[0,1]
	v_pk_mul_f32 v[128:129], v[16:17], v[128:129]
	v_pk_mul_f32 v[130:131], v[18:19], v[130:131]
	v_pk_mul_f32 v[132:133], v[20:21], v[132:133]
	v_pk_mul_f32 v[134:135], v[22:23], v[134:135]
	v_pk_mul_f32 v[136:137], v[24:25], v[136:137]
	v_pk_mul_f32 v[138:139], v[26:27], v[138:139]
	v_pk_mul_f32 v[140:141], v[28:29], v[140:141]
	v_pk_mul_f32 v[142:143], v[30:31], v[142:143]
	v_pk_fma_f32 v[128:129], v[48:49], v[128:129], v[32:33]
	v_pk_fma_f32 v[130:131], v[50:51], v[130:131], v[34:35]
	v_pk_fma_f32 v[132:133], v[52:53], v[132:133], v[36:37]
	v_pk_fma_f32 v[134:135], v[54:55], v[134:135], v[38:39]
	v_pk_fma_f32 v[136:137], v[56:57], v[136:137], v[40:41]
	v_pk_fma_f32 v[138:139], v[58:59], v[138:139], v[42:43]
	v_pk_fma_f32 v[140:141], v[60:61], v[140:141], v[44:45]
	v_pk_fma_f32 v[142:143], v[62:63], v[142:143], v[46:47]
	v_cvt_pk_bf16_f32 v176, v128, v129
	v_cvt_pk_bf16_f32 v177, v130, v131
	v_cvt_pk_bf16_f32 v178, v132, v133
	v_cvt_pk_bf16_f32 v179, v134, v135
	v_cvt_pk_bf16_f32 v180, v136, v137
	v_cvt_pk_bf16_f32 v181, v138, v139
	v_cvt_pk_bf16_f32 v182, v140, v141
	v_cvt_pk_bf16_f32 v183, v142, v143
	s_mov_b32 s10, s98
	s_lshl_b32 s10, s10, 11
	s_add_u32 s28, s26, s10
	s_addc_u32 s29, s27, 0
	global_store_dwordx4 v2, v[176:179], s[28:29] sc1
	global_store_dwordx4 v2, v[180:183], s[28:29] offset:1024 sc1
	v_pk_mul_f32 v[144:145], v[162:163], v[144:145] op_sel_hi:[0,1]
	v_pk_mul_f32 v[146:147], v[162:163], v[146:147] op_sel_hi:[0,1]
	v_pk_mul_f32 v[148:149], v[162:163], v[148:149] op_sel_hi:[0,1]
	v_pk_mul_f32 v[150:151], v[162:163], v[150:151] op_sel_hi:[0,1]
	v_pk_mul_f32 v[152:153], v[162:163], v[152:153] op_sel_hi:[0,1]
	v_pk_mul_f32 v[154:155], v[162:163], v[154:155] op_sel_hi:[0,1]
	v_pk_mul_f32 v[156:157], v[162:163], v[156:157] op_sel_hi:[0,1]
	v_pk_mul_f32 v[158:159], v[162:163], v[158:159] op_sel_hi:[0,1]
	v_pk_mul_f32 v[144:145], v[16:17], v[144:145]
	v_pk_mul_f32 v[146:147], v[18:19], v[146:147]
	v_pk_mul_f32 v[148:149], v[20:21], v[148:149]
	v_pk_mul_f32 v[150:151], v[22:23], v[150:151]
	v_pk_mul_f32 v[152:153], v[24:25], v[152:153]
	v_pk_mul_f32 v[154:155], v[26:27], v[154:155]
	v_pk_mul_f32 v[156:157], v[28:29], v[156:157]
	v_pk_mul_f32 v[158:159], v[30:31], v[158:159]
	v_pk_fma_f32 v[144:145], v[48:49], v[144:145], v[32:33]
	v_pk_fma_f32 v[146:147], v[50:51], v[146:147], v[34:35]
	v_pk_fma_f32 v[148:149], v[52:53], v[148:149], v[36:37]
	v_pk_fma_f32 v[150:151], v[54:55], v[150:151], v[38:39]
	v_pk_fma_f32 v[152:153], v[56:57], v[152:153], v[40:41]
	v_pk_fma_f32 v[154:155], v[58:59], v[154:155], v[42:43]
	v_pk_fma_f32 v[156:157], v[60:61], v[156:157], v[44:45]
	v_pk_fma_f32 v[158:159], v[62:63], v[158:159], v[46:47]
	v_cvt_pk_bf16_f32 v184, v144, v145
	v_cvt_pk_bf16_f32 v185, v146, v147
	v_cvt_pk_bf16_f32 v186, v148, v149
	v_cvt_pk_bf16_f32 v187, v150, v151
	v_cvt_pk_bf16_f32 v188, v152, v153
	v_cvt_pk_bf16_f32 v189, v154, v155
	v_cvt_pk_bf16_f32 v190, v156, v157
	v_cvt_pk_bf16_f32 v191, v158, v159
	s_add_i32 s10, s98, 0x1
	s_lshl_b32 s10, s10, 11
	s_add_u32 s28, s26, s10
	s_addc_u32 s29, s27, 0
	global_store_dwordx4 v2, v[184:187], s[28:29] sc1
	global_store_dwordx4 v2, v[188:191], s[28:29] offset:1024 sc1
	s_add_i32 s10, s98, 0x8
	s_lshl_b32 s10, s10, 11
	s_add_u32 s28, s22, s10
	s_addc_u32 s29, s23, 0
	global_load_dwordx4 v[64:67], v2, s[28:29]
	global_load_dwordx4 v[68:71], v2, s[28:29] offset:1024
	s_add_i32 s10, s98, 0x9
	s_lshl_b32 s10, s10, 11
	s_add_u32 s28, s22, s10
	s_addc_u32 s29, s23, 0
	global_load_dwordx4 v[72:75], v2, s[28:29]
	global_load_dwordx4 v[76:79], v2, s[28:29] offset:1024
	s_waitcnt vmcnt(16)
; __device__ __forceinline__ unsigned cvt_pk_bf16(float lo, float hi) { unsigned r; asm volatile("v_cvt_pk_bf16_f32 %0, %1, %2" : "=v"(r) : "v"(lo), "v"(hi)); return r; }
; __device__ __forceinline__ void norm_phase(const Params& P, unsigned char* ws, int layer, int which, int nrows, bool first, int lane, int wave, const float* pend_part, int pend_ns, const float* pend_gate) {
;     ...
; #pragma unroll
;         for (int r = 0; r < NR; ++r) { const int row = row0 + r * NGW;
;             const float rstd = rsqrtf(wave_sum(ss[r], lane) * (1.0f / DM) + EPS);
;             const float* mod = (const float*)(ws + WS_MOD) + (size_t)(layer * 9 + (row >> 12)) * 6144 + which * 3 * DM;
; #pragma unroll
;             for (int j = 0; j < 2; ++j) { const int col = 8 * lane + 512 * j; u32x4 hw, xw;
; #pragma unroll
;                 for (int q = 0; q < 2; ++q) {
;                     const f32x4 g4 = *(const f32x4*)(g + col + 4 * q), sh = *(const f32x4*)(mod + col + 4 * q), sc = *(const f32x4*)(mod + DM + col + 4 * q);
;                     const f32x4 h = (v[r][j][q] * rstd) * g4 * (sc + 1.0f) + sh;
;                     if (q == 0) { hw.x = cvt_pk_bf16(h[0], h[1]); hw.y = cvt_pk_bf16(h[2], h[3]); xw.x = cvt_pk_bf16(v[r][j][q][0], v[r][j][q][1]); xw.y = cvt_pk_bf16(v[r][j][q][2], v[r][j][q][3]); }
;                     else { hw.z = cvt_pk_bf16(h[0], h[1]); hw.w = cvt_pk_bf16(h[2], h[3]); xw.z = cvt_pk_bf16(v[r][j][q][0], v[r][j][q][1]); xw.w = cvt_pk_bf16(v[r][j][q][2], v[r][j][q][3]); }
;                 }
;                 *(u32x4*)(H + (size_t)row * DM + col) = hw;
;                 if (first) *(u32x4*)(XB + (size_t)row * DM + col) = xw;
;             } }
	v_lshlrev_b32_e32 v128, 16, v80
	v_and_b32_e32 v129, 0xffff0000, v80
	v_lshlrev_b32_e32 v130, 16, v81
	v_and_b32_e32 v131, 0xffff0000, v81
	v_lshlrev_b32_e32 v132, 16, v82
	v_and_b32_e32 v133, 0xffff0000, v82
	v_lshlrev_b32_e32 v134, 16, v83
	v_and_b32_e32 v135, 0xffff0000, v83
	v_lshlrev_b32_e32 v136, 16, v84
	v_and_b32_e32 v137, 0xffff0000, v84
	v_lshlrev_b32_e32 v138, 16, v85
	v_and_b32_e32 v139, 0xffff0000, v85
	v_lshlrev_b32_e32 v140, 16, v86
	v_and_b32_e32 v141, 0xffff0000, v86
	v_lshlrev_b32_e32 v142, 16, v87
	v_and_b32_e32 v143, 0xffff0000, v87
	v_lshlrev_b32_e32 v144, 16, v88
	v_and_b32_e32 v145, 0xffff0000, v88
	v_lshlrev_b32_e32 v146, 16, v89
	v_and_b32_e32 v147, 0xffff0000, v89
	v_lshlrev_b32_e32 v148, 16, v90
	v_and_b32_e32 v149, 0xffff0000, v90
	v_lshlrev_b32_e32 v150, 16, v91
	v_and_b32_e32 v151, 0xffff0000, v91
	v_lshlrev_b32_e32 v152, 16, v92
	v_and_b32_e32 v153, 0xffff0000, v92
	v_lshlrev_b32_e32 v154, 16, v93
	v_and_b32_e32 v155, 0xffff0000, v93
	v_lshlrev_b32_e32 v156, 16, v94
	v_and_b32_e32 v157, 0xffff0000, v94
	v_lshlrev_b32_e32 v158, 16, v95
	v_and_b32_e32 v159, 0xffff0000, v95
	v_pk_mul_f32 v[160:161], v[128:129], v[128:129]
	v_pk_mul_f32 v[162:163], v[144:145], v[144:145]
	v_pk_fma_f32 v[160:161], v[130:131], v[130:131], v[160:161]
	v_pk_fma_f32 v[162:163], v[146:147], v[146:147], v[162:163]
	v_pk_fma_f32 v[160:161], v[132:133], v[132:133], v[160:161]
	v_pk_fma_f32 v[162:163], v[148:149], v[148:149], v[162:163]
	v_pk_fma_f32 v[160:161], v[134:135], v[134:135], v[160:161]
	v_pk_fma_f32 v[162:163], v[150:151], v[150:151], v[162:163]
	v_pk_fma_f32 v[160:161], v[136:137], v[136:137], v[160:161]
	v_pk_fma_f32 v[162:163], v[152:153], v[152:153], v[162:163]
	v_pk_fma_f32 v[160:161], v[138:139], v[138:139], v[160:161]
	v_pk_fma_f32 v[162:163], v[154:155], v[154:155], v[162:163]
	v_pk_fma_f32 v[160:161], v[140:141], v[140:141], v[160:161]
	v_pk_fma_f32 v[162:163], v[156:157], v[156:157], v[162:163]
	v_pk_fma_f32 v[160:161], v[142:143], v[142:143], v[160:161]
	v_pk_fma_f32 v[162:163], v[158:159], v[158:159], v[162:163]
	v_add_f32_e32 v160, v160, v161
	v_add_f32_e32 v162, v162, v163
	ds_bpermute_b32 v164, v5, v160
	ds_bpermute_b32 v165, v5, v162
	s_waitcnt lgkmcnt(0)
	v_add_f32_e32 v160, v160, v164
	v_add_f32_e32 v162, v162, v165
	ds_bpermute_b32 v164, v6, v160
	ds_bpermute_b32 v165, v6, v162
	s_waitcnt lgkmcnt(0)
	v_add_f32_e32 v160, v160, v164
	v_add_f32_e32 v162, v162, v165
	ds_bpermute_b32 v164, v7, v160
	ds_bpermute_b32 v165, v7, v162
	s_waitcnt lgkmcnt(0)
	v_add_f32_e32 v160, v160, v164
	v_add_f32_e32 v162, v162, v165
	ds_bpermute_b32 v164, v9, v160
	ds_bpermute_b32 v165, v9, v162
	s_waitcnt lgkmcnt(0)
	v_add_f32_e32 v160, v160, v164
	v_add_f32_e32 v162, v162, v165
	ds_bpermute_b32 v164, v10, v160
	ds_bpermute_b32 v165, v10, v162
	s_waitcnt lgkmcnt(0)
	v_add_f32_e32 v160, v160, v164
	v_add_f32_e32 v162, v162, v165
	ds_bpermute_b32 v164, v11, v160
	ds_bpermute_b32 v165, v11, v162
	s_waitcnt lgkmcnt(0)
	v_add_f32_e32 v160, v160, v164
	v_add_f32_e32 v162, v162, v165
	v_fmamk_f32 v160, v160, 0x3a800000, v194
	v_fmamk_f32 v162, v162, 0x3a800000, v194
	v_rsq_f32_e32 v160, v160
	v_rsq_f32_e32 v162, v162
	s_nop 0
	v_pk_mul_f32 v[128:129], v[160:161], v[128:129] op_sel_hi:[0,1]
	v_pk_mul_f32 v[130:131], v[160:161], v[130:131] op_sel_hi:[0,1]
	v_pk_mul_f32 v[132:133], v[160:161], v[132:133] op_sel_hi:[0,1]
	v_pk_mul_f32 v[134:135], v[160:161], v[134:135] op_sel_hi:[0,1]
	v_pk_mul_f32 v[136:137], v[160:161], v[136:137] op_sel_hi:[0,1]
	v_pk_mul_f32 v[138:139], v[160:161], v[138:139] op_sel_hi:[0,1]
	v_pk_mul_f32 v[140:141], v[160:161], v[140:141] op_sel_hi:[0,1]
	v_pk_mul_f32 v[142:143], v[160:161], v[142:143] op_sel_hi:[0,1]
	v_pk_mul_f32 v[128:129], v[16:17], v[128:129]
	v_pk_mul_f32 v[130:131], v[18:19], v[130:131]
	v_pk_mul_f32 v[132:133], v[20:21], v[132:133]
	v_pk_mul_f32 v[134:135], v[22:23], v[134:135]
	v_pk_mul_f32 v[136:137], v[24:25], v[136:137]
	v_pk_mul_f32 v[138:139], v[26:27], v[138:139]
	v_pk_mul_f32 v[140:141], v[28:29], v[140:141]
	v_pk_mul_f32 v[142:143], v[30:31], v[142:143]
	v_pk_fma_f32 v[128:129], v[48:49], v[128:129], v[32:33]
	v_pk_fma_f32 v[130:131], v[50:51], v[130:131], v[34:35]
	v_pk_fma_f32 v[132:133], v[52:53], v[132:133], v[36:37]
	v_pk_fma_f32 v[134:135], v[54:55], v[134:135], v[38:39]
	v_pk_fma_f32 v[136:137], v[56:57], v[136:137], v[40:41]
	v_pk_fma_f32 v[138:139], v[58:59], v[138:139], v[42:43]
	v_pk_fma_f32 v[140:141], v[60:61], v[140:141], v[44:45]
	v_pk_fma_f32 v[142:143], v[62:63], v[142:143], v[46:47]
	v_cvt_pk_bf16_f32 v176, v128, v129
	v_cvt_pk_bf16_f32 v177, v130, v131
	v_cvt_pk_bf16_f32 v178, v132, v133
	v_cvt_pk_bf16_f32 v179, v134, v135
	v_cvt_pk_bf16_f32 v180, v136, v137
	v_cvt_pk_bf16_f32 v181, v138, v139
	v_cvt_pk_bf16_f32 v182, v140, v141
	v_cvt_pk_bf16_f32 v183, v142, v143
	s_add_i32 s10, s98, 0x2
	s_lshl_b32 s10, s10, 11
	s_add_u32 s28, s26, s10
	s_addc_u32 s29, s27, 0
	global_store_dwordx4 v2, v[176:179], s[28:29] sc1
	global_store_dwordx4 v2, v[180:183], s[28:29] offset:1024 sc1
	v_pk_mul_f32 v[144:145], v[162:163], v[144:145] op_sel_hi:[0,1]
	v_pk_mul_f32 v[146:147], v[162:163], v[146:147] op_sel_hi:[0,1]
	v_pk_mul_f32 v[148:149], v[162:163], v[148:149] op_sel_hi:[0,1]
	v_pk_mul_f32 v[150:151], v[162:163], v[150:151] op_sel_hi:[0,1]
	v_pk_mul_f32 v[152:153], v[162:163], v[152:153] op_sel_hi:[0,1]
	v_pk_mul_f32 v[154:155], v[162:163], v[154:155] op_sel_hi:[0,1]
	v_pk_mul_f32 v[156:157], v[162:163], v[156:157] op_sel_hi:[0,1]
	v_pk_mul_f32 v[158:159], v[162:163], v[158:159] op_sel_hi:[0,1]
	v_pk_mul_f32 v[144:145], v[16:17], v[144:145]
	v_pk_mul_f32 v[146:147], v[18:19], v[146:147]
; __device__ __forceinline__ unsigned cvt_pk_bf16(float lo, float hi) { unsigned r; asm volatile("v_cvt_pk_bf16_f32 %0, %1, %2" : "=v"(r) : "v"(lo), "v"(hi)); return r; }
; __device__ __forceinline__ void norm_phase(const Params& P, unsigned char* ws, int layer, int which, int nrows, bool first, int lane, int wave, const float* pend_part, int pend_ns, const float* pend_gate) {
;     ...
; #pragma unroll
;         for (int r = 0; r < NR; ++r) { const int row = row0 + r * NGW;
;             const float rstd = rsqrtf(wave_sum(ss[r], lane) * (1.0f / DM) + EPS);
;             const float* mod = (const float*)(ws + WS_MOD) + (size_t)(layer * 9 + (row >> 12)) * 6144 + which * 3 * DM;
; #pragma unroll
;             for (int j = 0; j < 2; ++j) { const int col = 8 * lane + 512 * j; u32x4 hw, xw;
; #pragma unroll
;                 for (int q = 0; q < 2; ++q) {
;                     const f32x4 g4 = *(const f32x4*)(g + col + 4 * q), sh = *(const f32x4*)(mod + col + 4 * q), sc = *(const f32x4*)(mod + DM + col + 4 * q);
;                     const f32x4 h = (v[r][j][q] * rstd) * g4 * (sc + 1.0f) + sh;
;                     if (q == 0) { hw.x = cvt_pk_bf16(h[0], h[1]); hw.y = cvt_pk_bf16(h[2], h[3]); xw.x = cvt_pk_bf16(v[r][j][q][0], v[r][j][q][1]); xw.y = cvt_pk_bf16(v[r][j][q][2], v[r][j][q][3]); }
;                     else { hw.z = cvt_pk_bf16(h[0], h[1]); hw.w = cvt_pk_bf16(h[2], h[3]); xw.z = cvt_pk_bf16(v[r][j][q][0], v[r][j][q][1]); xw.w = cvt_pk_bf16(v[r][j][q][2], v[r][j][q][3]); }
;                 }
;                 *(u32x4*)(H + (size_t)row * DM + col) = hw;
;                 if (first) *(u32x4*)(XB + (size_t)row * DM + col) = xw;
;             } }
	v_pk_mul_f32 v[148:149], v[20:21], v[148:149]
	v_pk_mul_f32 v[150:151], v[22:23], v[150:151]
	v_pk_mul_f32 v[152:153], v[24:25], v[152:153]
	v_pk_mul_f32 v[154:155], v[26:27], v[154:155]
	v_pk_mul_f32 v[156:157], v[28:29], v[156:157]
	v_pk_mul_f32 v[158:159], v[30:31], v[158:159]
	v_pk_fma_f32 v[144:145], v[48:49], v[144:145], v[32:33]
	v_pk_fma_f32 v[146:147], v[50:51], v[146:147], v[34:35]
	v_pk_fma_f32 v[148:149], v[52:53], v[148:149], v[36:37]
	v_pk_fma_f32 v[150:151], v[54:55], v[150:151], v[38:39]
	v_pk_fma_f32 v[152:153], v[56:57], v[152:153], v[40:41]
	v_pk_fma_f32 v[154:155], v[58:59], v[154:155], v[42:43]
	v_pk_fma_f32 v[156:157], v[60:61], v[156:157], v[44:45]
	v_pk_fma_f32 v[158:159], v[62:63], v[158:159], v[46:47]
	v_cvt_pk_bf16_f32 v184, v144, v145
	v_cvt_pk_bf16_f32 v185, v146, v147
	v_cvt_pk_bf16_f32 v186, v148, v149
	v_cvt_pk_bf16_f32 v187, v150, v151
	v_cvt_pk_bf16_f32 v188, v152, v153
	v_cvt_pk_bf16_f32 v189, v154, v155
	v_cvt_pk_bf16_f32 v190, v156, v157
	v_cvt_pk_bf16_f32 v191, v158, v159
	s_add_i32 s10, s98, 0x3
	s_lshl_b32 s10, s10, 11
	s_add_u32 s28, s26, s10
	s_addc_u32 s29, s27, 0
	global_store_dwordx4 v2, v[184:187], s[28:29] sc1
	global_store_dwordx4 v2, v[188:191], s[28:29] offset:1024 sc1
	s_add_i32 s10, s98, 0xa
	s_lshl_b32 s10, s10, 11
	s_add_u32 s28, s22, s10
	s_addc_u32 s29, s23, 0
	global_load_dwordx4 v[80:83], v2, s[28:29]
	global_load_dwordx4 v[84:87], v2, s[28:29] offset:1024
	s_add_i32 s10, s98, 0xb
	s_lshl_b32 s10, s10, 11
	s_add_u32 s28, s22, s10
	s_addc_u32 s29, s23, 0
	global_load_dwordx4 v[88:91], v2, s[28:29]
	global_load_dwordx4 v[92:95], v2, s[28:29] offset:1024
	s_waitcnt vmcnt(20)
	v_lshlrev_b32_e32 v128, 16, v96
	v_and_b32_e32 v129, 0xffff0000, v96
	v_lshlrev_b32_e32 v130, 16, v97
	v_and_b32_e32 v131, 0xffff0000, v97
	v_lshlrev_b32_e32 v132, 16, v98
	v_and_b32_e32 v133, 0xffff0000, v98
	v_lshlrev_b32_e32 v134, 16, v99
	v_and_b32_e32 v135, 0xffff0000, v99
	v_lshlrev_b32_e32 v136, 16, v100
	v_and_b32_e32 v137, 0xffff0000, v100
	v_lshlrev_b32_e32 v138, 16, v101
	v_and_b32_e32 v139, 0xffff0000, v101
	v_lshlrev_b32_e32 v140, 16, v102
	v_and_b32_e32 v141, 0xffff0000, v102
	v_lshlrev_b32_e32 v142, 16, v103
	v_and_b32_e32 v143, 0xffff0000, v103
	v_lshlrev_b32_e32 v144, 16, v104
	v_and_b32_e32 v145, 0xffff0000, v104
	v_lshlrev_b32_e32 v146, 16, v105
	v_and_b32_e32 v147, 0xffff0000, v105
	v_lshlrev_b32_e32 v148, 16, v106
	v_and_b32_e32 v149, 0xffff0000, v106
	v_lshlrev_b32_e32 v150, 16, v107
	v_and_b32_e32 v151, 0xffff0000, v107
	v_lshlrev_b32_e32 v152, 16, v108
	v_and_b32_e32 v153, 0xffff0000, v108
	v_lshlrev_b32_e32 v154, 16, v109
	v_and_b32_e32 v155, 0xffff0000, v109
	v_lshlrev_b32_e32 v156, 16, v110
	v_and_b32_e32 v157, 0xffff0000, v110
	v_lshlrev_b32_e32 v158, 16, v111
	v_and_b32_e32 v159, 0xffff0000, v111
	v_pk_mul_f32 v[160:161], v[128:129], v[128:129]
	v_pk_mul_f32 v[162:163], v[144:145], v[144:145]
	v_pk_fma_f32 v[160:161], v[130:131], v[130:131], v[160:161]
	v_pk_fma_f32 v[162:163], v[146:147], v[146:147], v[162:163]
	v_pk_fma_f32 v[160:161], v[132:133], v[132:133], v[160:161]
	v_pk_fma_f32 v[162:163], v[148:149], v[148:149], v[162:163]
	v_pk_fma_f32 v[160:161], v[134:135], v[134:135], v[160:161]
	v_pk_fma_f32 v[162:163], v[150:151], v[150:151], v[162:163]
	v_pk_fma_f32 v[160:161], v[136:137], v[136:137], v[160:161]
	v_pk_fma_f32 v[162:163], v[152:153], v[152:153], v[162:163]
	v_pk_fma_f32 v[160:161], v[138:139], v[138:139], v[160:161]
	v_pk_fma_f32 v[162:163], v[154:155], v[154:155], v[162:163]
	v_pk_fma_f32 v[160:161], v[140:141], v[140:141], v[160:161]
	v_pk_fma_f32 v[162:163], v[156:157], v[156:157], v[162:163]
	v_pk_fma_f32 v[160:161], v[142:143], v[142:143], v[160:161]
	v_pk_fma_f32 v[162:163], v[158:159], v[158:159], v[162:163]
	v_add_f32_e32 v160, v160, v161
	v_add_f32_e32 v162, v162, v163
	ds_bpermute_b32 v164, v5, v160
	ds_bpermute_b32 v165, v5, v162
	s_waitcnt lgkmcnt(0)
	v_add_f32_e32 v160, v160, v164
	v_add_f32_e32 v162, v162, v165
	ds_bpermute_b32 v164, v6, v160
	ds_bpermute_b32 v165, v6, v162
	s_waitcnt lgkmcnt(0)
	v_add_f32_e32 v160, v160, v164
	v_add_f32_e32 v162, v162, v165
	ds_bpermute_b32 v164, v7, v160
	ds_bpermute_b32 v165, v7, v162
	s_waitcnt lgkmcnt(0)
	v_add_f32_e32 v160, v160, v164
	v_add_f32_e32 v162, v162, v165
	ds_bpermute_b32 v164, v9, v160
	ds_bpermute_b32 v165, v9, v162
	s_waitcnt lgkmcnt(0)
	v_add_f32_e32 v160, v160, v164
	v_add_f32_e32 v162, v162, v165
	ds_bpermute_b32 v164, v10, v160
	ds_bpermute_b32 v165, v10, v162
	s_waitcnt lgkmcnt(0)
	v_add_f32_e32 v160, v160, v164
	v_add_f32_e32 v162, v162, v165
	ds_bpermute_b32 v164, v11, v160
	ds_bpermute_b32 v165, v11, v162
	s_waitcnt lgkmcnt(0)
; __device__ __forceinline__ unsigned cvt_pk_bf16(float lo, float hi) { unsigned r; asm volatile("v_cvt_pk_bf16_f32 %0, %1, %2" : "=v"(r) : "v"(lo), "v"(hi)); return r; }
; __device__ __forceinline__ void norm_phase(const Params& P, unsigned char* ws, int layer, int which, int nrows, bool first, int lane, int wave, const float* pend_part, int pend_ns, const float* pend_gate) {
;     ...
; #pragma unroll
;         for (int r = 0; r < NR; ++r) { const int row = row0 + r * NGW;
;             const float rstd = rsqrtf(wave_sum(ss[r], lane) * (1.0f / DM) + EPS);
;             const float* mod = (const float*)(ws + WS_MOD) + (size_t)(layer * 9 + (row >> 12)) * 6144 + which * 3 * DM;
; #pragma unroll
;             for (int j = 0; j < 2; ++j) { const int col = 8 * lane + 512 * j; u32x4 hw, xw;
; #pragma unroll
;                 for (int q = 0; q < 2; ++q) {
;                     const f32x4 g4 = *(const f32x4*)(g + col + 4 * q), sh = *(const f32x4*)(mod + col + 4 * q), sc = *(const f32x4*)(mod + DM + col + 4 * q);
;                     const f32x4 h = (v[r][j][q] * rstd) * g4 * (sc + 1.0f) + sh;
;                     if (q == 0) { hw.x = cvt_pk_bf16(h[0], h[1]); hw.y = cvt_pk_bf16(h[2], h[3]); xw.x = cvt_pk_bf16(v[r][j][q][0], v[r][j][q][1]); xw.y = cvt_pk_bf16(v[r][j][q][2], v[r][j][q][3]); }
;                     else { hw.z = cvt_pk_bf16(h[0], h[1]); hw.w = cvt_pk_bf16(h[2], h[3]); xw.z = cvt_pk_bf16(v[r][j][q][0], v[r][j][q][1]); xw.w = cvt_pk_bf16(v[r][j][q][2], v[r][j][q][3]); }
;                 }
;                 *(u32x4*)(H + (size_t)row * DM + col) = hw;
;                 if (first) *(u32x4*)(XB + (size_t)row * DM + col) = xw;
;             } }
	v_add_f32_e32 v160, v160, v164
	v_add_f32_e32 v162, v162, v165
	v_fmamk_f32 v160, v160, 0x3a800000, v194
	v_fmamk_f32 v162, v162, 0x3a800000, v194
	v_rsq_f32_e32 v160, v160
	v_rsq_f32_e32 v162, v162
	s_nop 0
	v_pk_mul_f32 v[128:129], v[160:161], v[128:129] op_sel_hi:[0,1]
	v_pk_mul_f32 v[130:131], v[160:161], v[130:131] op_sel_hi:[0,1]
	v_pk_mul_f32 v[132:133], v[160:161], v[132:133] op_sel_hi:[0,1]
	v_pk_mul_f32 v[134:135], v[160:161], v[134:135] op_sel_hi:[0,1]
	v_pk_mul_f32 v[136:137], v[160:161], v[136:137] op_sel_hi:[0,1]
	v_pk_mul_f32 v[138:139], v[160:161], v[138:139] op_sel_hi:[0,1]
	v_pk_mul_f32 v[140:141], v[160:161], v[140:141] op_sel_hi:[0,1]
	v_pk_mul_f32 v[142:143], v[160:161], v[142:143] op_sel_hi:[0,1]
	v_pk_mul_f32 v[128:129], v[16:17], v[128:129]
	v_pk_mul_f32 v[130:131], v[18:19], v[130:131]
	v_pk_mul_f32 v[132:133], v[20:21], v[132:133]
	v_pk_mul_f32 v[134:135], v[22:23], v[134:135]
	v_pk_mul_f32 v[136:137], v[24:25], v[136:137]
	v_pk_mul_f32 v[138:139], v[26:27], v[138:139]
	v_pk_mul_f32 v[140:141], v[28:29], v[140:141]
	v_pk_mul_f32 v[142:143], v[30:31], v[142:143]
	v_pk_fma_f32 v[128:129], v[48:49], v[128:129], v[32:33]
	v_pk_fma_f32 v[130:131], v[50:51], v[130:131], v[34:35]
	v_pk_fma_f32 v[132:133], v[52:53], v[132:133], v[36:37]
	v_pk_fma_f32 v[134:135], v[54:55], v[134:135], v[38:39]
	v_pk_fma_f32 v[136:137], v[56:57], v[136:137], v[40:41]
	v_pk_fma_f32 v[138:139], v[58:59], v[138:139], v[42:43]
	v_pk_fma_f32 v[140:141], v[60:61], v[140:141], v[44:45]
	v_pk_fma_f32 v[142:143], v[62:63], v[142:143], v[46:47]
	v_cvt_pk_bf16_f32 v176, v128, v129
	v_cvt_pk_bf16_f32 v177, v130, v131
	v_cvt_pk_bf16_f32 v178, v132, v133
	v_cvt_pk_bf16_f32 v179, v134, v135
	v_cvt_pk_bf16_f32 v180, v136, v137
	v_cvt_pk_bf16_f32 v181, v138, v139
	v_cvt_pk_bf16_f32 v182, v140, v141
	v_cvt_pk_bf16_f32 v183, v142, v143
	s_add_i32 s10, s98, 0x4
	s_lshl_b32 s10, s10, 11
	s_add_u32 s28, s26, s10
	s_addc_u32 s29, s27, 0
	global_store_dwordx4 v2, v[176:179], s[28:29] sc1
	global_store_dwordx4 v2, v[180:183], s[28:29] offset:1024 sc1
	v_pk_mul_f32 v[144:145], v[162:163], v[144:145] op_sel_hi:[0,1]
	v_pk_mul_f32 v[146:147], v[162:163], v[146:147] op_sel_hi:[0,1]
	v_pk_mul_f32 v[148:149], v[162:163], v[148:149] op_sel_hi:[0,1]
	v_pk_mul_f32 v[150:151], v[162:163], v[150:151] op_sel_hi:[0,1]
	v_pk_mul_f32 v[152:153], v[162:163], v[152:153] op_sel_hi:[0,1]
	v_pk_mul_f32 v[154:155], v[162:163], v[154:155] op_sel_hi:[0,1]
	v_pk_mul_f32 v[156:157], v[162:163], v[156:157] op_sel_hi:[0,1]
	v_pk_mul_f32 v[158:159], v[162:163], v[158:159] op_sel_hi:[0,1]
	v_pk_mul_f32 v[144:145], v[16:17], v[144:145]
	v_pk_mul_f32 v[146:147], v[18:19], v[146:147]
	v_pk_mul_f32 v[148:149], v[20:21], v[148:149]
	v_pk_mul_f32 v[150:151], v[22:23], v[150:151]
	v_pk_mul_f32 v[152:153], v[24:25], v[152:153]
	v_pk_mul_f32 v[154:155], v[26:27], v[154:155]
	v_pk_mul_f32 v[156:157], v[28:29], v[156:157]
	v_pk_mul_f32 v[158:159], v[30:31], v[158:159]
	v_pk_fma_f32 v[144:145], v[48:49], v[144:145], v[32:33]
	v_pk_fma_f32 v[146:147], v[50:51], v[146:147], v[34:35]
	v_pk_fma_f32 v[148:149], v[52:53], v[148:149], v[36:37]
	v_pk_fma_f32 v[150:151], v[54:55], v[150:151], v[38:39]
	v_pk_fma_f32 v[152:153], v[56:57], v[152:153], v[40:41]
	v_pk_fma_f32 v[154:155], v[58:59], v[154:155], v[42:43]
	v_pk_fma_f32 v[156:157], v[60:61], v[156:157], v[44:45]
	v_pk_fma_f32 v[158:159], v[62:63], v[158:159], v[46:47]
	v_cvt_pk_bf16_f32 v184, v144, v145
	v_cvt_pk_bf16_f32 v185, v146, v147
	v_cvt_pk_bf16_f32 v186, v148, v149
	v_cvt_pk_bf16_f32 v187, v150, v151
	v_cvt_pk_bf16_f32 v188, v152, v153
	v_cvt_pk_bf16_f32 v189, v154, v155
	v_cvt_pk_bf16_f32 v190, v156, v157
	v_cvt_pk_bf16_f32 v191, v158, v159
	s_add_i32 s10, s98, 0x5
	s_lshl_b32 s10, s10, 11
	s_add_u32 s28, s26, s10
	s_addc_u32 s29, s27, 0
	global_store_dwordx4 v2, v[184:187], s[28:29] sc1
	global_store_dwordx4 v2, v[188:191], s[28:29] offset:1024 sc1
	s_add_i32 s10, s98, 0xc
	s_lshl_b32 s10, s10, 11
	s_add_u32 s28, s22, s10
	s_addc_u32 s29, s23, 0
	global_load_dwordx4 v[96:99], v2, s[28:29]
	global_load_dwordx4 v[100:103], v2, s[28:29] offset:1024
	s_add_i32 s10, s98, 0xd
	s_lshl_b32 s10, s10, 11
	s_add_u32 s28, s22, s10
	s_addc_u32 s29, s23, 0
	global_load_dwordx4 v[104:107], v2, s[28:29]
	global_load_dwordx4 v[108:111], v2, s[28:29] offset:1024
	s_waitcnt vmcnt(24)
	v_lshlrev_b32_e32 v128, 16, v112
	v_and_b32_e32 v129, 0xffff0000, v112
	v_lshlrev_b32_e32 v130, 16, v113
	v_and_b32_e32 v131, 0xffff0000, v113
	v_lshlrev_b32_e32 v132, 16, v114
	v_and_b32_e32 v133, 0xffff0000, v114
	v_lshlrev_b32_e32 v134, 16, v115
	v_and_b32_e32 v135, 0xffff0000, v115
	v_lshlrev_b32_e32 v136, 16, v116
	v_and_b32_e32 v137, 0xffff0000, v116
	v_lshlrev_b32_e32 v138, 16, v117
	v_and_b32_e32 v139, 0xffff0000, v117
	v_lshlrev_b32_e32 v140, 16, v118
	v_and_b32_e32 v141, 0xffff0000, v118
	v_lshlrev_b32_e32 v142, 16, v119
	v_and_b32_e32 v143, 0xffff0000, v119
	v_lshlrev_b32_e32 v144, 16, v120
	v_and_b32_e32 v145, 0xffff0000, v120
	v_lshlrev_b32_e32 v146, 16, v121
	v_and_b32_e32 v147, 0xffff0000, v121
	v_lshlrev_b32_e32 v148, 16, v122
	v_and_b32_e32 v149, 0xffff0000, v122
	v_lshlrev_b32_e32 v150, 16, v123
	v_and_b32_e32 v151, 0xffff0000, v123
	v_lshlrev_b32_e32 v152, 16, v124
	v_and_b32_e32 v153, 0xffff0000, v124
	v_lshlrev_b32_e32 v154, 16, v125
	v_and_b32_e32 v155, 0xffff0000, v125
	v_lshlrev_b32_e32 v156, 16, v126
	v_and_b32_e32 v157, 0xffff0000, v126
	v_lshlrev_b32_e32 v158, 16, v127
	v_and_b32_e32 v159, 0xffff0000, v127
	v_pk_mul_f32 v[160:161], v[128:129], v[128:129]
	v_pk_mul_f32 v[162:163], v[144:145], v[144:145]
	v_pk_fma_f32 v[160:161], v[130:131], v[130:131], v[160:161]
	v_pk_fma_f32 v[162:163], v[146:147], v[146:147], v[162:163]
	v_pk_fma_f32 v[160:161], v[132:133], v[132:133], v[160:161]
	v_pk_fma_f32 v[162:163], v[148:149], v[148:149], v[162:163]
	v_pk_fma_f32 v[160:161], v[134:135], v[134:135], v[160:161]
	v_pk_fma_f32 v[162:163], v[150:151], v[150:151], v[162:163]
	v_pk_fma_f32 v[160:161], v[136:137], v[136:137], v[160:161]
	v_pk_fma_f32 v[162:163], v[152:153], v[152:153], v[162:163]
	v_pk_fma_f32 v[160:161], v[138:139], v[138:139], v[160:161]
	v_pk_fma_f32 v[162:163], v[154:155], v[154:155], v[162:163]
	v_pk_fma_f32 v[160:161], v[140:141], v[140:141], v[160:161]
	v_pk_fma_f32 v[162:163], v[156:157], v[156:157], v[162:163]
	v_pk_fma_f32 v[160:161], v[142:143], v[142:143], v[160:161]
	v_pk_fma_f32 v[162:163], v[158:159], v[158:159], v[162:163]
	v_add_f32_e32 v160, v160, v161
	v_add_f32_e32 v162, v162, v163
	ds_bpermute_b32 v164, v5, v160
	ds_bpermute_b32 v165, v5, v162
	s_waitcnt lgkmcnt(0)
; __device__ __forceinline__ unsigned cvt_pk_bf16(float lo, float hi) { unsigned r; asm volatile("v_cvt_pk_bf16_f32 %0, %1, %2" : "=v"(r) : "v"(lo), "v"(hi)); return r; }
; __device__ __forceinline__ void norm_phase(const Params& P, unsigned char* ws, int layer, int which, int nrows, bool first, int lane, int wave, const float* pend_part, int pend_ns, const float* pend_gate) {
;     ...
; #pragma unroll
;         for (int r = 0; r < NR; ++r) { const int row = row0 + r * NGW;
;             const float rstd = rsqrtf(wave_sum(ss[r], lane) * (1.0f / DM) + EPS);
;             const float* mod = (const float*)(ws + WS_MOD) + (size_t)(layer * 9 + (row >> 12)) * 6144 + which * 3 * DM;
; #pragma unroll
;             for (int j = 0; j < 2; ++j) { const int col = 8 * lane + 512 * j; u32x4 hw, xw;
; #pragma unroll
;                 for (int q = 0; q < 2; ++q) {
;                     const f32x4 g4 = *(const f32x4*)(g + col + 4 * q), sh = *(const f32x4*)(mod + col + 4 * q), sc = *(const f32x4*)(mod + DM + col + 4 * q);
;                     const f32x4 h = (v[r][j][q] * rstd) * g4 * (sc + 1.0f) + sh;
;                     if (q == 0) { hw.x = cvt_pk_bf16(h[0], h[1]); hw.y = cvt_pk_bf16(h[2], h[3]); xw.x = cvt_pk_bf16(v[r][j][q][0], v[r][j][q][1]); xw.y = cvt_pk_bf16(v[r][j][q][2], v[r][j][q][3]); }
;                     else { hw.z = cvt_pk_bf16(h[0], h[1]); hw.w = cvt_pk_bf16(h[2], h[3]); xw.z = cvt_pk_bf16(v[r][j][q][0], v[r][j][q][1]); xw.w = cvt_pk_bf16(v[r][j][q][2], v[r][j][q][3]); }
;                 }
;                 *(u32x4*)(H + (size_t)row * DM + col) = hw;
;                 if (first) *(u32x4*)(XB + (size_t)row * DM + col) = xw;
;             } }
	v_add_f32_e32 v160, v160, v164
	v_add_f32_e32 v162, v162, v165
	ds_bpermute_b32 v164, v6, v160
	ds_bpermute_b32 v165, v6, v162
	s_waitcnt lgkmcnt(0)
	v_add_f32_e32 v160, v160, v164
	v_add_f32_e32 v162, v162, v165
	ds_bpermute_b32 v164, v7, v160
	ds_bpermute_b32 v165, v7, v162
	s_waitcnt lgkmcnt(0)
	v_add_f32_e32 v160, v160, v164
	v_add_f32_e32 v162, v162, v165
	ds_bpermute_b32 v164, v9, v160
	ds_bpermute_b32 v165, v9, v162
	s_waitcnt lgkmcnt(0)
	v_add_f32_e32 v160, v160, v164
	v_add_f32_e32 v162, v162, v165
	ds_bpermute_b32 v164, v10, v160
	ds_bpermute_b32 v165, v10, v162
	s_waitcnt lgkmcnt(0)
	v_add_f32_e32 v160, v160, v164
	v_add_f32_e32 v162, v162, v165
	ds_bpermute_b32 v164, v11, v160
	ds_bpermute_b32 v165, v11, v162
	s_waitcnt lgkmcnt(0)
	v_add_f32_e32 v160, v160, v164
	v_add_f32_e32 v162, v162, v165
	v_fmamk_f32 v160, v160, 0x3a800000, v194
	v_fmamk_f32 v162, v162, 0x3a800000, v194
	v_rsq_f32_e32 v160, v160
	v_rsq_f32_e32 v162, v162
	s_nop 0
	v_pk_mul_f32 v[128:129], v[160:161], v[128:129] op_sel_hi:[0,1]
	v_pk_mul_f32 v[130:131], v[160:161], v[130:131] op_sel_hi:[0,1]
	v_pk_mul_f32 v[132:133], v[160:161], v[132:133] op_sel_hi:[0,1]
	v_pk_mul_f32 v[134:135], v[160:161], v[134:135] op_sel_hi:[0,1]
	v_pk_mul_f32 v[136:137], v[160:161], v[136:137] op_sel_hi:[0,1]
	v_pk_mul_f32 v[138:139], v[160:161], v[138:139] op_sel_hi:[0,1]
	v_pk_mul_f32 v[140:141], v[160:161], v[140:141] op_sel_hi:[0,1]
	v_pk_mul_f32 v[142:143], v[160:161], v[142:143] op_sel_hi:[0,1]
	v_pk_mul_f32 v[128:129], v[16:17], v[128:129]
	v_pk_mul_f32 v[130:131], v[18:19], v[130:131]
	v_pk_mul_f32 v[132:133], v[20:21], v[132:133]
	v_pk_mul_f32 v[134:135], v[22:23], v[134:135]
	v_pk_mul_f32 v[136:137], v[24:25], v[136:137]
	v_pk_mul_f32 v[138:139], v[26:27], v[138:139]
	v_pk_mul_f32 v[140:141], v[28:29], v[140:141]
	v_pk_mul_f32 v[142:143], v[30:31], v[142:143]
	v_pk_fma_f32 v[128:129], v[48:49], v[128:129], v[32:33]
	v_pk_fma_f32 v[130:131], v[50:51], v[130:131], v[34:35]
	v_pk_fma_f32 v[132:133], v[52:53], v[132:133], v[36:37]
	v_pk_fma_f32 v[134:135], v[54:55], v[134:135], v[38:39]
	v_pk_fma_f32 v[136:137], v[56:57], v[136:137], v[40:41]
	v_pk_fma_f32 v[138:139], v[58:59], v[138:139], v[42:43]
	v_pk_fma_f32 v[140:141], v[60:61], v[140:141], v[44:45]
	v_pk_fma_f32 v[142:143], v[62:63], v[142:143], v[46:47]
	v_cvt_pk_bf16_f32 v176, v128, v129
	v_cvt_pk_bf16_f32 v177, v130, v131
	v_cvt_pk_bf16_f32 v178, v132, v133
	v_cvt_pk_bf16_f32 v179, v134, v135
	v_cvt_pk_bf16_f32 v180, v136, v137
	v_cvt_pk_bf16_f32 v181, v138, v139
	v_cvt_pk_bf16_f32 v182, v140, v141
	v_cvt_pk_bf16_f32 v183, v142, v143
	s_add_i32 s10, s98, 0x6
	s_lshl_b32 s10, s10, 11
	s_add_u32 s28, s26, s10
	s_addc_u32 s29, s27, 0
	global_store_dwordx4 v2, v[176:179], s[28:29] sc1
	global_store_dwordx4 v2, v[180:183], s[28:29] offset:1024 sc1
	v_pk_mul_f32 v[144:145], v[162:163], v[144:145] op_sel_hi:[0,1]
	v_pk_mul_f32 v[146:147], v[162:163], v[146:147] op_sel_hi:[0,1]
	v_pk_mul_f32 v[148:149], v[162:163], v[148:149] op_sel_hi:[0,1]
	v_pk_mul_f32 v[150:151], v[162:163], v[150:151] op_sel_hi:[0,1]
	v_pk_mul_f32 v[152:153], v[162:163], v[152:153] op_sel_hi:[0,1]
	v_pk_mul_f32 v[154:155], v[162:163], v[154:155] op_sel_hi:[0,1]
	v_pk_mul_f32 v[156:157], v[162:163], v[156:157] op_sel_hi:[0,1]
	v_pk_mul_f32 v[158:159], v[162:163], v[158:159] op_sel_hi:[0,1]
	v_pk_mul_f32 v[144:145], v[16:17], v[144:145]
	v_pk_mul_f32 v[146:147], v[18:19], v[146:147]
	v_pk_mul_f32 v[148:149], v[20:21], v[148:149]
	v_pk_mul_f32 v[150:151], v[22:23], v[150:151]
	v_pk_mul_f32 v[152:153], v[24:25], v[152:153]
	v_pk_mul_f32 v[154:155], v[26:27], v[154:155]
	v_pk_mul_f32 v[156:157], v[28:29], v[156:157]
	v_pk_mul_f32 v[158:159], v[30:31], v[158:159]
	v_pk_fma_f32 v[144:145], v[48:49], v[144:145], v[32:33]
	v_pk_fma_f32 v[146:147], v[50:51], v[146:147], v[34:35]
	v_pk_fma_f32 v[148:149], v[52:53], v[148:149], v[36:37]
	v_pk_fma_f32 v[150:151], v[54:55], v[150:151], v[38:39]
	v_pk_fma_f32 v[152:153], v[56:57], v[152:153], v[40:41]
	v_pk_fma_f32 v[154:155], v[58:59], v[154:155], v[42:43]
	v_pk_fma_f32 v[156:157], v[60:61], v[156:157], v[44:45]
	v_pk_fma_f32 v[158:159], v[62:63], v[158:159], v[46:47]
	v_cvt_pk_bf16_f32 v184, v144, v145
	v_cvt_pk_bf16_f32 v185, v146, v147
	v_cvt_pk_bf16_f32 v186, v148, v149
	v_cvt_pk_bf16_f32 v187, v150, v151
	v_cvt_pk_bf16_f32 v188, v152, v153
	v_cvt_pk_bf16_f32 v189, v154, v155
	v_cvt_pk_bf16_f32 v190, v156, v157
	v_cvt_pk_bf16_f32 v191, v158, v159
	s_add_i32 s10, s98, 0x7
	s_lshl_b32 s10, s10, 11
	s_add_u32 s28, s26, s10
	s_addc_u32 s29, s27, 0
	global_store_dwordx4 v2, v[184:187], s[28:29] sc1
	global_store_dwordx4 v2, v[188:191], s[28:29] offset:1024 sc1
	s_add_i32 s10, s98, 0xe
	s_lshl_b32 s10, s10, 11
	s_add_u32 s28, s22, s10
	s_addc_u32 s29, s23, 0
	global_load_dwordx4 v[112:115], v2, s[28:29]
	global_load_dwordx4 v[116:119], v2, s[28:29] offset:1024
	s_add_i32 s10, s98, 0xf
	s_lshl_b32 s10, s10, 11
	s_add_u32 s28, s22, s10
	s_addc_u32 s29, s23, 0
	global_load_dwordx4 v[120:123], v2, s[28:29]
	global_load_dwordx4 v[124:127], v2, s[28:29] offset:1024
	s_waitcnt vmcnt(24)
; __device__ __forceinline__ unsigned cvt_pk_bf16(float lo, float hi) { unsigned r; asm volatile("v_cvt_pk_bf16_f32 %0, %1, %2" : "=v"(r) : "v"(lo), "v"(hi)); return r; }
; __device__ __forceinline__ void norm_phase(const Params& P, unsigned char* ws, int layer, int which, int nrows, bool first, int lane, int wave, const float* pend_part, int pend_ns, const float* pend_gate) {
;     ...
; #pragma unroll
;         for (int r = 0; r < NR; ++r) { const int row = row0 + r * NGW;
;             const float rstd = rsqrtf(wave_sum(ss[r], lane) * (1.0f / DM) + EPS);
;             const float* mod = (const float*)(ws + WS_MOD) + (size_t)(layer * 9 + (row >> 12)) * 6144 + which * 3 * DM;
; #pragma unroll
;             for (int j = 0; j < 2; ++j) { const int col = 8 * lane + 512 * j; u32x4 hw, xw;
; #pragma unroll
;                 for (int q = 0; q < 2; ++q) {
;                     const f32x4 g4 = *(const f32x4*)(g + col + 4 * q), sh = *(const f32x4*)(mod + col + 4 * q), sc = *(const f32x4*)(mod + DM + col + 4 * q);
;                     const f32x4 h = (v[r][j][q] * rstd) * g4 * (sc + 1.0f) + sh;
;                     if (q == 0) { hw.x = cvt_pk_bf16(h[0], h[1]); hw.y = cvt_pk_bf16(h[2], h[3]); xw.x = cvt_pk_bf16(v[r][j][q][0], v[r][j][q][1]); xw.y = cvt_pk_bf16(v[r][j][q][2], v[r][j][q][3]); }
;                     else { hw.z = cvt_pk_bf16(h[0], h[1]); hw.w = cvt_pk_bf16(h[2], h[3]); xw.z = cvt_pk_bf16(v[r][j][q][0], v[r][j][q][1]); xw.w = cvt_pk_bf16(v[r][j][q][2], v[r][j][q][3]); }
;                 }
;                 *(u32x4*)(H + (size_t)row * DM + col) = hw;
;                 if (first) *(u32x4*)(XB + (size_t)row * DM + col) = xw;
;             } }
	v_lshlrev_b32_e32 v128, 16, v64
	v_and_b32_e32 v129, 0xffff0000, v64
	v_lshlrev_b32_e32 v130, 16, v65
	v_and_b32_e32 v131, 0xffff0000, v65
	v_lshlrev_b32_e32 v132, 16, v66
	v_and_b32_e32 v133, 0xffff0000, v66
	v_lshlrev_b32_e32 v134, 16, v67
	v_and_b32_e32 v135, 0xffff0000, v67
	v_lshlrev_b32_e32 v136, 16, v68
	v_and_b32_e32 v137, 0xffff0000, v68
	v_lshlrev_b32_e32 v138, 16, v69
	v_and_b32_e32 v139, 0xffff0000, v69
	v_lshlrev_b32_e32 v140, 16, v70
	v_and_b32_e32 v141, 0xffff0000, v70
	v_lshlrev_b32_e32 v142, 16, v71
	v_and_b32_e32 v143, 0xffff0000, v71
	v_lshlrev_b32_e32 v144, 16, v72
	v_and_b32_e32 v145, 0xffff0000, v72
	v_lshlrev_b32_e32 v146, 16, v73
	v_and_b32_e32 v147, 0xffff0000, v73
	v_lshlrev_b32_e32 v148, 16, v74
	v_and_b32_e32 v149, 0xffff0000, v74
	v_lshlrev_b32_e32 v150, 16, v75
	v_and_b32_e32 v151, 0xffff0000, v75
	v_lshlrev_b32_e32 v152, 16, v76
	v_and_b32_e32 v153, 0xffff0000, v76
	v_lshlrev_b32_e32 v154, 16, v77
	v_and_b32_e32 v155, 0xffff0000, v77
	v_lshlrev_b32_e32 v156, 16, v78
	v_and_b32_e32 v157, 0xffff0000, v78
	v_lshlrev_b32_e32 v158, 16, v79
	v_and_b32_e32 v159, 0xffff0000, v79
	v_pk_mul_f32 v[160:161], v[128:129], v[128:129]
	v_pk_mul_f32 v[162:163], v[144:145], v[144:145]
	v_pk_fma_f32 v[160:161], v[130:131], v[130:131], v[160:161]
	v_pk_fma_f32 v[162:163], v[146:147], v[146:147], v[162:163]
	v_pk_fma_f32 v[160:161], v[132:133], v[132:133], v[160:161]
	v_pk_fma_f32 v[162:163], v[148:149], v[148:149], v[162:163]
	v_pk_fma_f32 v[160:161], v[134:135], v[134:135], v[160:161]
	v_pk_fma_f32 v[162:163], v[150:151], v[150:151], v[162:163]
	v_pk_fma_f32 v[160:161], v[136:137], v[136:137], v[160:161]
	v_pk_fma_f32 v[162:163], v[152:153], v[152:153], v[162:163]
	v_pk_fma_f32 v[160:161], v[138:139], v[138:139], v[160:161]
	v_pk_fma_f32 v[162:163], v[154:155], v[154:155], v[162:163]
	v_pk_fma_f32 v[160:161], v[140:141], v[140:141], v[160:161]
	v_pk_fma_f32 v[162:163], v[156:157], v[156:157], v[162:163]
	v_pk_fma_f32 v[160:161], v[142:143], v[142:143], v[160:161]
	v_pk_fma_f32 v[162:163], v[158:159], v[158:159], v[162:163]
	v_add_f32_e32 v160, v160, v161
	v_add_f32_e32 v162, v162, v163
	ds_bpermute_b32 v164, v5, v160
	ds_bpermute_b32 v165, v5, v162
	s_waitcnt lgkmcnt(0)
	v_add_f32_e32 v160, v160, v164
	v_add_f32_e32 v162, v162, v165
	ds_bpermute_b32 v164, v6, v160
	ds_bpermute_b32 v165, v6, v162
	s_waitcnt lgkmcnt(0)
	v_add_f32_e32 v160, v160, v164
	v_add_f32_e32 v162, v162, v165
	ds_bpermute_b32 v164, v7, v160
	ds_bpermute_b32 v165, v7, v162
	s_waitcnt lgkmcnt(0)
	v_add_f32_e32 v160, v160, v164
	v_add_f32_e32 v162, v162, v165
	ds_bpermute_b32 v164, v9, v160
	ds_bpermute_b32 v165, v9, v162
	s_waitcnt lgkmcnt(0)
	v_add_f32_e32 v160, v160, v164
	v_add_f32_e32 v162, v162, v165
	ds_bpermute_b32 v164, v10, v160
	ds_bpermute_b32 v165, v10, v162
	s_waitcnt lgkmcnt(0)
	v_add_f32_e32 v160, v160, v164
	v_add_f32_e32 v162, v162, v165
	ds_bpermute_b32 v164, v11, v160
	ds_bpermute_b32 v165, v11, v162
	s_waitcnt lgkmcnt(0)
	v_add_f32_e32 v160, v160, v164
	v_add_f32_e32 v162, v162, v165
	v_fmamk_f32 v160, v160, 0x3a800000, v194
	v_fmamk_f32 v162, v162, 0x3a800000, v194
	v_rsq_f32_e32 v160, v160
	v_rsq_f32_e32 v162, v162
	s_nop 0
	v_pk_mul_f32 v[128:129], v[160:161], v[128:129] op_sel_hi:[0,1]
	v_pk_mul_f32 v[130:131], v[160:161], v[130:131] op_sel_hi:[0,1]
	v_pk_mul_f32 v[132:133], v[160:161], v[132:133] op_sel_hi:[0,1]
	v_pk_mul_f32 v[134:135], v[160:161], v[134:135] op_sel_hi:[0,1]
	v_pk_mul_f32 v[136:137], v[160:161], v[136:137] op_sel_hi:[0,1]
	v_pk_mul_f32 v[138:139], v[160:161], v[138:139] op_sel_hi:[0,1]
	v_pk_mul_f32 v[140:141], v[160:161], v[140:141] op_sel_hi:[0,1]
	v_pk_mul_f32 v[142:143], v[160:161], v[142:143] op_sel_hi:[0,1]
	v_pk_mul_f32 v[128:129], v[16:17], v[128:129]
	v_pk_mul_f32 v[130:131], v[18:19], v[130:131]
	v_pk_mul_f32 v[132:133], v[20:21], v[132:133]
	v_pk_mul_f32 v[134:135], v[22:23], v[134:135]
	v_pk_mul_f32 v[136:137], v[24:25], v[136:137]
	v_pk_mul_f32 v[138:139], v[26:27], v[138:139]
	v_pk_mul_f32 v[140:141], v[28:29], v[140:141]
	v_pk_mul_f32 v[142:143], v[30:31], v[142:143]
	v_pk_fma_f32 v[128:129], v[48:49], v[128:129], v[32:33]
	v_pk_fma_f32 v[130:131], v[50:51], v[130:131], v[34:35]
	v_pk_fma_f32 v[132:133], v[52:53], v[132:133], v[36:37]
	v_pk_fma_f32 v[134:135], v[54:55], v[134:135], v[38:39]
	v_pk_fma_f32 v[136:137], v[56:57], v[136:137], v[40:41]
	v_pk_fma_f32 v[138:139], v[58:59], v[138:139], v[42:43]
	v_pk_fma_f32 v[140:141], v[60:61], v[140:141], v[44:45]
	v_pk_fma_f32 v[142:143], v[62:63], v[142:143], v[46:47]
	v_cvt_pk_bf16_f32 v176, v128, v129
	v_cvt_pk_bf16_f32 v177, v130, v131
	v_cvt_pk_bf16_f32 v178, v132, v133
	v_cvt_pk_bf16_f32 v179, v134, v135
	v_cvt_pk_bf16_f32 v180, v136, v137
	v_cvt_pk_bf16_f32 v181, v138, v139
	v_cvt_pk_bf16_f32 v182, v140, v141
	v_cvt_pk_bf16_f32 v183, v142, v143
	s_add_i32 s10, s98, 0x8
	s_lshl_b32 s10, s10, 11
	s_add_u32 s28, s26, s10
	s_addc_u32 s29, s27, 0
	global_store_dwordx4 v2, v[176:179], s[28:29] sc1
	global_store_dwordx4 v2, v[180:183], s[28:29] offset:1024 sc1
	v_pk_mul_f32 v[144:145], v[162:163], v[144:145] op_sel_hi:[0,1]
	v_pk_mul_f32 v[146:147], v[162:163], v[146:147] op_sel_hi:[0,1]
	v_pk_mul_f32 v[148:149], v[162:163], v[148:149] op_sel_hi:[0,1]
	v_pk_mul_f32 v[150:151], v[162:163], v[150:151] op_sel_hi:[0,1]
	v_pk_mul_f32 v[152:153], v[162:163], v[152:153] op_sel_hi:[0,1]
	v_pk_mul_f32 v[154:155], v[162:163], v[154:155] op_sel_hi:[0,1]
	v_pk_mul_f32 v[156:157], v[162:163], v[156:157] op_sel_hi:[0,1]
	v_pk_mul_f32 v[158:159], v[162:163], v[158:159] op_sel_hi:[0,1]
	v_pk_mul_f32 v[144:145], v[16:17], v[144:145]
	v_pk_mul_f32 v[146:147], v[18:19], v[146:147]
	v_pk_mul_f32 v[148:149], v[20:21], v[148:149]
	v_pk_mul_f32 v[150:151], v[22:23], v[150:151]
	v_pk_mul_f32 v[152:153], v[24:25], v[152:153]
	v_pk_mul_f32 v[154:155], v[26:27], v[154:155]
	v_pk_mul_f32 v[156:157], v[28:29], v[156:157]
	v_pk_mul_f32 v[158:159], v[30:31], v[158:159]
	v_pk_fma_f32 v[144:145], v[48:49], v[144:145], v[32:33]
	v_pk_fma_f32 v[146:147], v[50:51], v[146:147], v[34:35]
	v_pk_fma_f32 v[148:149], v[52:53], v[148:149], v[36:37]
	v_pk_fma_f32 v[150:151], v[54:55], v[150:151], v[38:39]
	v_pk_fma_f32 v[152:153], v[56:57], v[152:153], v[40:41]
	v_pk_fma_f32 v[154:155], v[58:59], v[154:155], v[42:43]
	v_pk_fma_f32 v[156:157], v[60:61], v[156:157], v[44:45]
	v_pk_fma_f32 v[158:159], v[62:63], v[158:159], v[46:47]
	v_cvt_pk_bf16_f32 v184, v144, v145
	v_cvt_pk_bf16_f32 v185, v146, v147
	v_cvt_pk_bf16_f32 v186, v148, v149
	v_cvt_pk_bf16_f32 v187, v150, v151
	v_cvt_pk_bf16_f32 v188, v152, v153
	v_cvt_pk_bf16_f32 v189, v154, v155
	v_cvt_pk_bf16_f32 v190, v156, v157
	v_cvt_pk_bf16_f32 v191, v158, v159
	s_add_i32 s10, s98, 0x9
	s_lshl_b32 s10, s10, 11
	s_add_u32 s28, s26, s10
	s_addc_u32 s29, s27, 0
	global_store_dwordx4 v2, v[184:187], s[28:29] sc1
	global_store_dwordx4 v2, v[188:191], s[28:29] offset:1024 sc1
	s_waitcnt vmcnt(20)
; __device__ __forceinline__ unsigned cvt_pk_bf16(float lo, float hi) { unsigned r; asm volatile("v_cvt_pk_bf16_f32 %0, %1, %2" : "=v"(r) : "v"(lo), "v"(hi)); return r; }
; __device__ __forceinline__ void norm_phase(const Params& P, unsigned char* ws, int layer, int which, int nrows, bool first, int lane, int wave, const float* pend_part, int pend_ns, const float* pend_gate) {
;     ...
; #pragma unroll
;         for (int r = 0; r < NR; ++r) { const int row = row0 + r * NGW;
;             const float rstd = rsqrtf(wave_sum(ss[r], lane) * (1.0f / DM) + EPS);
;             const float* mod = (const float*)(ws + WS_MOD) + (size_t)(layer * 9 + (row >> 12)) * 6144 + which * 3 * DM;
; #pragma unroll
;             for (int j = 0; j < 2; ++j) { const int col = 8 * lane + 512 * j; u32x4 hw, xw;
; #pragma unroll
;                 for (int q = 0; q < 2; ++q) {
;                     const f32x4 g4 = *(const f32x4*)(g + col + 4 * q), sh = *(const f32x4*)(mod + col + 4 * q), sc = *(const f32x4*)(mod + DM + col + 4 * q);
;                     const f32x4 h = (v[r][j][q] * rstd) * g4 * (sc + 1.0f) + sh;
;                     if (q == 0) { hw.x = cvt_pk_bf16(h[0], h[1]); hw.y = cvt_pk_bf16(h[2], h[3]); xw.x = cvt_pk_bf16(v[r][j][q][0], v[r][j][q][1]); xw.y = cvt_pk_bf16(v[r][j][q][2], v[r][j][q][3]); }
;                     else { hw.z = cvt_pk_bf16(h[0], h[1]); hw.w = cvt_pk_bf16(h[2], h[3]); xw.z = cvt_pk_bf16(v[r][j][q][0], v[r][j][q][1]); xw.w = cvt_pk_bf16(v[r][j][q][2], v[r][j][q][3]); }
;                 }
;                 *(u32x4*)(H + (size_t)row * DM + col) = hw;
;                 if (first) *(u32x4*)(XB + (size_t)row * DM + col) = xw;
;             } }
	v_lshlrev_b32_e32 v128, 16, v80
	v_and_b32_e32 v129, 0xffff0000, v80
	v_lshlrev_b32_e32 v130, 16, v81
	v_and_b32_e32 v131, 0xffff0000, v81
	v_lshlrev_b32_e32 v132, 16, v82
	v_and_b32_e32 v133, 0xffff0000, v82
	v_lshlrev_b32_e32 v134, 16, v83
	v_and_b32_e32 v135, 0xffff0000, v83
	v_lshlrev_b32_e32 v136, 16, v84
	v_and_b32_e32 v137, 0xffff0000, v84
	v_lshlrev_b32_e32 v138, 16, v85
	v_and_b32_e32 v139, 0xffff0000, v85
	v_lshlrev_b32_e32 v140, 16, v86
	v_and_b32_e32 v141, 0xffff0000, v86
	v_lshlrev_b32_e32 v142, 16, v87
	v_and_b32_e32 v143, 0xffff0000, v87
	v_lshlrev_b32_e32 v144, 16, v88
	v_and_b32_e32 v145, 0xffff0000, v88
	v_lshlrev_b32_e32 v146, 16, v89
	v_and_b32_e32 v147, 0xffff0000, v89
	v_lshlrev_b32_e32 v148, 16, v90
	v_and_b32_e32 v149, 0xffff0000, v90
	v_lshlrev_b32_e32 v150, 16, v91
	v_and_b32_e32 v151, 0xffff0000, v91
	v_lshlrev_b32_e32 v152, 16, v92
	v_and_b32_e32 v153, 0xffff0000, v92
	v_lshlrev_b32_e32 v154, 16, v93
	v_and_b32_e32 v155, 0xffff0000, v93
	v_lshlrev_b32_e32 v156, 16, v94
	v_and_b32_e32 v157, 0xffff0000, v94
	v_lshlrev_b32_e32 v158, 16, v95
	v_and_b32_e32 v159, 0xffff0000, v95
	v_pk_mul_f32 v[160:161], v[128:129], v[128:129]
	v_pk_mul_f32 v[162:163], v[144:145], v[144:145]
	v_pk_fma_f32 v[160:161], v[130:131], v[130:131], v[160:161]
	v_pk_fma_f32 v[162:163], v[146:147], v[146:147], v[162:163]
	v_pk_fma_f32 v[160:161], v[132:133], v[132:133], v[160:161]
	v_pk_fma_f32 v[162:163], v[148:149], v[148:149], v[162:163]
	v_pk_fma_f32 v[160:161], v[134:135], v[134:135], v[160:161]
	v_pk_fma_f32 v[162:163], v[150:151], v[150:151], v[162:163]
	v_pk_fma_f32 v[160:161], v[136:137], v[136:137], v[160:161]
	v_pk_fma_f32 v[162:163], v[152:153], v[152:153], v[162:163]
	v_pk_fma_f32 v[160:161], v[138:139], v[138:139], v[160:161]
	v_pk_fma_f32 v[162:163], v[154:155], v[154:155], v[162:163]
	v_pk_fma_f32 v[160:161], v[140:141], v[140:141], v[160:161]
	v_pk_fma_f32 v[162:163], v[156:157], v[156:157], v[162:163]
	v_pk_fma_f32 v[160:161], v[142:143], v[142:143], v[160:161]
	v_pk_fma_f32 v[162:163], v[158:159], v[158:159], v[162:163]
	v_add_f32_e32 v160, v160, v161
	v_add_f32_e32 v162, v162, v163
	ds_bpermute_b32 v164, v5, v160
	ds_bpermute_b32 v165, v5, v162
	s_waitcnt lgkmcnt(0)
	v_add_f32_e32 v160, v160, v164
	v_add_f32_e32 v162, v162, v165
	ds_bpermute_b32 v164, v6, v160
	ds_bpermute_b32 v165, v6, v162
	s_waitcnt lgkmcnt(0)
	v_add_f32_e32 v160, v160, v164
	v_add_f32_e32 v162, v162, v165
	ds_bpermute_b32 v164, v7, v160
	ds_bpermute_b32 v165, v7, v162
	s_waitcnt lgkmcnt(0)
	v_add_f32_e32 v160, v160, v164
	v_add_f32_e32 v162, v162, v165
	ds_bpermute_b32 v164, v9, v160
	ds_bpermute_b32 v165, v9, v162
	s_waitcnt lgkmcnt(0)
	v_add_f32_e32 v160, v160, v164
	v_add_f32_e32 v162, v162, v165
	ds_bpermute_b32 v164, v10, v160
	ds_bpermute_b32 v165, v10, v162
	s_waitcnt lgkmcnt(0)
	v_add_f32_e32 v160, v160, v164
	v_add_f32_e32 v162, v162, v165
	ds_bpermute_b32 v164, v11, v160
	ds_bpermute_b32 v165, v11, v162
	s_waitcnt lgkmcnt(0)
	v_add_f32_e32 v160, v160, v164
	v_add_f32_e32 v162, v162, v165
	v_fmamk_f32 v160, v160, 0x3a800000, v194
	v_fmamk_f32 v162, v162, 0x3a800000, v194
	v_rsq_f32_e32 v160, v160
	v_rsq_f32_e32 v162, v162
	s_nop 0
	v_pk_mul_f32 v[128:129], v[160:161], v[128:129] op_sel_hi:[0,1]
	v_pk_mul_f32 v[130:131], v[160:161], v[130:131] op_sel_hi:[0,1]
	v_pk_mul_f32 v[132:133], v[160:161], v[132:133] op_sel_hi:[0,1]
	v_pk_mul_f32 v[134:135], v[160:161], v[134:135] op_sel_hi:[0,1]
	v_pk_mul_f32 v[136:137], v[160:161], v[136:137] op_sel_hi:[0,1]
	v_pk_mul_f32 v[138:139], v[160:161], v[138:139] op_sel_hi:[0,1]
	v_pk_mul_f32 v[140:141], v[160:161], v[140:141] op_sel_hi:[0,1]
	v_pk_mul_f32 v[142:143], v[160:161], v[142:143] op_sel_hi:[0,1]
	v_pk_mul_f32 v[128:129], v[16:17], v[128:129]
	v_pk_mul_f32 v[130:131], v[18:19], v[130:131]
	v_pk_mul_f32 v[132:133], v[20:21], v[132:133]
	v_pk_mul_f32 v[134:135], v[22:23], v[134:135]
	v_pk_mul_f32 v[136:137], v[24:25], v[136:137]
	v_pk_mul_f32 v[138:139], v[26:27], v[138:139]
	v_pk_mul_f32 v[140:141], v[28:29], v[140:141]
	v_pk_mul_f32 v[142:143], v[30:31], v[142:143]
	v_pk_fma_f32 v[128:129], v[48:49], v[128:129], v[32:33]
	v_pk_fma_f32 v[130:131], v[50:51], v[130:131], v[34:35]
	v_pk_fma_f32 v[132:133], v[52:53], v[132:133], v[36:37]
	v_pk_fma_f32 v[134:135], v[54:55], v[134:135], v[38:39]
	v_pk_fma_f32 v[136:137], v[56:57], v[136:137], v[40:41]
	v_pk_fma_f32 v[138:139], v[58:59], v[138:139], v[42:43]
	v_pk_fma_f32 v[140:141], v[60:61], v[140:141], v[44:45]
	v_pk_fma_f32 v[142:143], v[62:63], v[142:143], v[46:47]
	v_cvt_pk_bf16_f32 v176, v128, v129
	v_cvt_pk_bf16_f32 v177, v130, v131
	v_cvt_pk_bf16_f32 v178, v132, v133
	v_cvt_pk_bf16_f32 v179, v134, v135
	v_cvt_pk_bf16_f32 v180, v136, v137
	v_cvt_pk_bf16_f32 v181, v138, v139
	v_cvt_pk_bf16_f32 v182, v140, v141
	v_cvt_pk_bf16_f32 v183, v142, v143
	s_add_i32 s10, s98, 0xa
	s_lshl_b32 s10, s10, 11
	s_add_u32 s28, s26, s10
	s_addc_u32 s29, s27, 0
	global_store_dwordx4 v2, v[176:179], s[28:29] sc1
	global_store_dwordx4 v2, v[180:183], s[28:29] offset:1024 sc1
	v_pk_mul_f32 v[144:145], v[162:163], v[144:145] op_sel_hi:[0,1]
	v_pk_mul_f32 v[146:147], v[162:163], v[146:147] op_sel_hi:[0,1]
	v_pk_mul_f32 v[148:149], v[162:163], v[148:149] op_sel_hi:[0,1]
	v_pk_mul_f32 v[150:151], v[162:163], v[150:151] op_sel_hi:[0,1]
	v_pk_mul_f32 v[152:153], v[162:163], v[152:153] op_sel_hi:[0,1]
	v_pk_mul_f32 v[154:155], v[162:163], v[154:155] op_sel_hi:[0,1]
	v_pk_mul_f32 v[156:157], v[162:163], v[156:157] op_sel_hi:[0,1]
	v_pk_mul_f32 v[158:159], v[162:163], v[158:159] op_sel_hi:[0,1]
	v_pk_mul_f32 v[144:145], v[16:17], v[144:145]
	v_pk_mul_f32 v[146:147], v[18:19], v[146:147]
	v_pk_mul_f32 v[148:149], v[20:21], v[148:149]
	v_pk_mul_f32 v[150:151], v[22:23], v[150:151]
	v_pk_mul_f32 v[152:153], v[24:25], v[152:153]
	v_pk_mul_f32 v[154:155], v[26:27], v[154:155]
	v_pk_mul_f32 v[156:157], v[28:29], v[156:157]
	v_pk_mul_f32 v[158:159], v[30:31], v[158:159]
	v_pk_fma_f32 v[144:145], v[48:49], v[144:145], v[32:33]
	v_pk_fma_f32 v[146:147], v[50:51], v[146:147], v[34:35]
	v_pk_fma_f32 v[148:149], v[52:53], v[148:149], v[36:37]
	v_pk_fma_f32 v[150:151], v[54:55], v[150:151], v[38:39]
	v_pk_fma_f32 v[152:153], v[56:57], v[152:153], v[40:41]
	v_pk_fma_f32 v[154:155], v[58:59], v[154:155], v[42:43]
	v_pk_fma_f32 v[156:157], v[60:61], v[156:157], v[44:45]
	v_pk_fma_f32 v[158:159], v[62:63], v[158:159], v[46:47]
	v_cvt_pk_bf16_f32 v184, v144, v145
	v_cvt_pk_bf16_f32 v185, v146, v147
	v_cvt_pk_bf16_f32 v186, v148, v149
	v_cvt_pk_bf16_f32 v187, v150, v151
	v_cvt_pk_bf16_f32 v188, v152, v153
	v_cvt_pk_bf16_f32 v189, v154, v155
	v_cvt_pk_bf16_f32 v190, v156, v157
	v_cvt_pk_bf16_f32 v191, v158, v159
	s_add_i32 s10, s98, 0xb
	s_lshl_b32 s10, s10, 11
	s_add_u32 s28, s26, s10
	s_addc_u32 s29, s27, 0
	global_store_dwordx4 v2, v[184:187], s[28:29] sc1
	global_store_dwordx4 v2, v[188:191], s[28:29] offset:1024 sc1
	s_waitcnt vmcnt(16)
; __device__ __forceinline__ unsigned cvt_pk_bf16(float lo, float hi) { unsigned r; asm volatile("v_cvt_pk_bf16_f32 %0, %1, %2" : "=v"(r) : "v"(lo), "v"(hi)); return r; }
; __device__ __forceinline__ void norm_phase(const Params& P, unsigned char* ws, int layer, int which, int nrows, bool first, int lane, int wave, const float* pend_part, int pend_ns, const float* pend_gate) {
;     ...
; #pragma unroll
;         for (int r = 0; r < NR; ++r) { const int row = row0 + r * NGW;
;             const float rstd = rsqrtf(wave_sum(ss[r], lane) * (1.0f / DM) + EPS);
;             const float* mod = (const float*)(ws + WS_MOD) + (size_t)(layer * 9 + (row >> 12)) * 6144 + which * 3 * DM;
; #pragma unroll
;             for (int j = 0; j < 2; ++j) { const int col = 8 * lane + 512 * j; u32x4 hw, xw;
; #pragma unroll
;                 for (int q = 0; q < 2; ++q) {
;                     const f32x4 g4 = *(const f32x4*)(g + col + 4 * q), sh = *(const f32x4*)(mod + col + 4 * q), sc = *(const f32x4*)(mod + DM + col + 4 * q);
;                     const f32x4 h = (v[r][j][q] * rstd) * g4 * (sc + 1.0f) + sh;
;                     if (q == 0) { hw.x = cvt_pk_bf16(h[0], h[1]); hw.y = cvt_pk_bf16(h[2], h[3]); xw.x = cvt_pk_bf16(v[r][j][q][0], v[r][j][q][1]); xw.y = cvt_pk_bf16(v[r][j][q][2], v[r][j][q][3]); }
;                     else { hw.z = cvt_pk_bf16(h[0], h[1]); hw.w = cvt_pk_bf16(h[2], h[3]); xw.z = cvt_pk_bf16(v[r][j][q][0], v[r][j][q][1]); xw.w = cvt_pk_bf16(v[r][j][q][2], v[r][j][q][3]); }
;                 }
;                 *(u32x4*)(H + (size_t)row * DM + col) = hw;
;                 if (first) *(u32x4*)(XB + (size_t)row * DM + col) = xw;
;             } }
	v_lshlrev_b32_e32 v128, 16, v96
	v_and_b32_e32 v129, 0xffff0000, v96
	v_lshlrev_b32_e32 v130, 16, v97
	v_and_b32_e32 v131, 0xffff0000, v97
	v_lshlrev_b32_e32 v132, 16, v98
	v_and_b32_e32 v133, 0xffff0000, v98
	v_lshlrev_b32_e32 v134, 16, v99
	v_and_b32_e32 v135, 0xffff0000, v99
	v_lshlrev_b32_e32 v136, 16, v100
	v_and_b32_e32 v137, 0xffff0000, v100
	v_lshlrev_b32_e32 v138, 16, v101
	v_and_b32_e32 v139, 0xffff0000, v101
	v_lshlrev_b32_e32 v140, 16, v102
	v_and_b32_e32 v141, 0xffff0000, v102
	v_lshlrev_b32_e32 v142, 16, v103
	v_and_b32_e32 v143, 0xffff0000, v103
	v_lshlrev_b32_e32 v144, 16, v104
	v_and_b32_e32 v145, 0xffff0000, v104
	v_lshlrev_b32_e32 v146, 16, v105
	v_and_b32_e32 v147, 0xffff0000, v105
	v_lshlrev_b32_e32 v148, 16, v106
	v_and_b32_e32 v149, 0xffff0000, v106
	v_lshlrev_b32_e32 v150, 16, v107
	v_and_b32_e32 v151, 0xffff0000, v107
	v_lshlrev_b32_e32 v152, 16, v108
	v_and_b32_e32 v153, 0xffff0000, v108
	v_lshlrev_b32_e32 v154, 16, v109
	v_and_b32_e32 v155, 0xffff0000, v109
	v_lshlrev_b32_e32 v156, 16, v110
	v_and_b32_e32 v157, 0xffff0000, v110
	v_lshlrev_b32_e32 v158, 16, v111
	v_and_b32_e32 v159, 0xffff0000, v111
	v_pk_mul_f32 v[160:161], v[128:129], v[128:129]
	v_pk_mul_f32 v[162:163], v[144:145], v[144:145]
	v_pk_fma_f32 v[160:161], v[130:131], v[130:131], v[160:161]
	v_pk_fma_f32 v[162:163], v[146:147], v[146:147], v[162:163]
	v_pk_fma_f32 v[160:161], v[132:133], v[132:133], v[160:161]
	v_pk_fma_f32 v[162:163], v[148:149], v[148:149], v[162:163]
	v_pk_fma_f32 v[160:161], v[134:135], v[134:135], v[160:161]
	v_pk_fma_f32 v[162:163], v[150:151], v[150:151], v[162:163]
	v_pk_fma_f32 v[160:161], v[136:137], v[136:137], v[160:161]
	v_pk_fma_f32 v[162:163], v[152:153], v[152:153], v[162:163]
	v_pk_fma_f32 v[160:161], v[138:139], v[138:139], v[160:161]
	v_pk_fma_f32 v[162:163], v[154:155], v[154:155], v[162:163]
	v_pk_fma_f32 v[160:161], v[140:141], v[140:141], v[160:161]
	v_pk_fma_f32 v[162:163], v[156:157], v[156:157], v[162:163]
	v_pk_fma_f32 v[160:161], v[142:143], v[142:143], v[160:161]
	v_pk_fma_f32 v[162:163], v[158:159], v[158:159], v[162:163]
	v_add_f32_e32 v160, v160, v161
	v_add_f32_e32 v162, v162, v163
	ds_bpermute_b32 v164, v5, v160
	ds_bpermute_b32 v165, v5, v162
	s_waitcnt lgkmcnt(0)
	v_add_f32_e32 v160, v160, v164
	v_add_f32_e32 v162, v162, v165
	ds_bpermute_b32 v164, v6, v160
	ds_bpermute_b32 v165, v6, v162
	s_waitcnt lgkmcnt(0)
	v_add_f32_e32 v160, v160, v164
	v_add_f32_e32 v162, v162, v165
	ds_bpermute_b32 v164, v7, v160
	ds_bpermute_b32 v165, v7, v162
	s_waitcnt lgkmcnt(0)
	v_add_f32_e32 v160, v160, v164
	v_add_f32_e32 v162, v162, v165
	ds_bpermute_b32 v164, v9, v160
	ds_bpermute_b32 v165, v9, v162
	s_waitcnt lgkmcnt(0)
	v_add_f32_e32 v160, v160, v164
	v_add_f32_e32 v162, v162, v165
	ds_bpermute_b32 v164, v10, v160
	ds_bpermute_b32 v165, v10, v162
	s_waitcnt lgkmcnt(0)
	v_add_f32_e32 v160, v160, v164
	v_add_f32_e32 v162, v162, v165
	ds_bpermute_b32 v164, v11, v160
	ds_bpermute_b32 v165, v11, v162
	s_waitcnt lgkmcnt(0)
	v_add_f32_e32 v160, v160, v164
	v_add_f32_e32 v162, v162, v165
	v_fmamk_f32 v160, v160, 0x3a800000, v194
	v_fmamk_f32 v162, v162, 0x3a800000, v194
	v_rsq_f32_e32 v160, v160
	v_rsq_f32_e32 v162, v162
	s_nop 0
	v_pk_mul_f32 v[128:129], v[160:161], v[128:129] op_sel_hi:[0,1]
	v_pk_mul_f32 v[130:131], v[160:161], v[130:131] op_sel_hi:[0,1]
	v_pk_mul_f32 v[132:133], v[160:161], v[132:133] op_sel_hi:[0,1]
	v_pk_mul_f32 v[134:135], v[160:161], v[134:135] op_sel_hi:[0,1]
	v_pk_mul_f32 v[136:137], v[160:161], v[136:137] op_sel_hi:[0,1]
	v_pk_mul_f32 v[138:139], v[160:161], v[138:139] op_sel_hi:[0,1]
	v_pk_mul_f32 v[140:141], v[160:161], v[140:141] op_sel_hi:[0,1]
	v_pk_mul_f32 v[142:143], v[160:161], v[142:143] op_sel_hi:[0,1]
	v_pk_mul_f32 v[128:129], v[16:17], v[128:129]
	v_pk_mul_f32 v[130:131], v[18:19], v[130:131]
	v_pk_mul_f32 v[132:133], v[20:21], v[132:133]
	v_pk_mul_f32 v[134:135], v[22:23], v[134:135]
	v_pk_mul_f32 v[136:137], v[24:25], v[136:137]
	v_pk_mul_f32 v[138:139], v[26:27], v[138:139]
	v_pk_mul_f32 v[140:141], v[28:29], v[140:141]
	v_pk_mul_f32 v[142:143], v[30:31], v[142:143]
	v_pk_fma_f32 v[128:129], v[48:49], v[128:129], v[32:33]
	v_pk_fma_f32 v[130:131], v[50:51], v[130:131], v[34:35]
	v_pk_fma_f32 v[132:133], v[52:53], v[132:133], v[36:37]
	v_pk_fma_f32 v[134:135], v[54:55], v[134:135], v[38:39]
	v_pk_fma_f32 v[136:137], v[56:57], v[136:137], v[40:41]
	v_pk_fma_f32 v[138:139], v[58:59], v[138:139], v[42:43]
	v_pk_fma_f32 v[140:141], v[60:61], v[140:141], v[44:45]
	v_pk_fma_f32 v[142:143], v[62:63], v[142:143], v[46:47]
	v_cvt_pk_bf16_f32 v176, v128, v129
	v_cvt_pk_bf16_f32 v177, v130, v131
	v_cvt_pk_bf16_f32 v178, v132, v133
	v_cvt_pk_bf16_f32 v179, v134, v135
	v_cvt_pk_bf16_f32 v180, v136, v137
	v_cvt_pk_bf16_f32 v181, v138, v139
	v_cvt_pk_bf16_f32 v182, v140, v141
	v_cvt_pk_bf16_f32 v183, v142, v143
	s_add_i32 s10, s98, 0xc
	s_lshl_b32 s10, s10, 11
	s_add_u32 s28, s26, s10
	s_addc_u32 s29, s27, 0
	global_store_dwordx4 v2, v[176:179], s[28:29] sc1
	global_store_dwordx4 v2, v[180:183], s[28:29] offset:1024 sc1
	v_pk_mul_f32 v[144:145], v[162:163], v[144:145] op_sel_hi:[0,1]
	v_pk_mul_f32 v[146:147], v[162:163], v[146:147] op_sel_hi:[0,1]
	v_pk_mul_f32 v[148:149], v[162:163], v[148:149] op_sel_hi:[0,1]
	v_pk_mul_f32 v[150:151], v[162:163], v[150:151] op_sel_hi:[0,1]
	v_pk_mul_f32 v[152:153], v[162:163], v[152:153] op_sel_hi:[0,1]
	v_pk_mul_f32 v[154:155], v[162:163], v[154:155] op_sel_hi:[0,1]
	v_pk_mul_f32 v[156:157], v[162:163], v[156:157] op_sel_hi:[0,1]
	v_pk_mul_f32 v[158:159], v[162:163], v[158:159] op_sel_hi:[0,1]
	v_pk_mul_f32 v[144:145], v[16:17], v[144:145]
	v_pk_mul_f32 v[146:147], v[18:19], v[146:147]
	v_pk_mul_f32 v[148:149], v[20:21], v[148:149]
	v_pk_mul_f32 v[150:151], v[22:23], v[150:151]
	v_pk_mul_f32 v[152:153], v[24:25], v[152:153]
	v_pk_mul_f32 v[154:155], v[26:27], v[154:155]
	v_pk_mul_f32 v[156:157], v[28:29], v[156:157]
	v_pk_mul_f32 v[158:159], v[30:31], v[158:159]
	v_pk_fma_f32 v[144:145], v[48:49], v[144:145], v[32:33]
	v_pk_fma_f32 v[146:147], v[50:51], v[146:147], v[34:35]
	v_pk_fma_f32 v[148:149], v[52:53], v[148:149], v[36:37]
	v_pk_fma_f32 v[150:151], v[54:55], v[150:151], v[38:39]
	v_pk_fma_f32 v[152:153], v[56:57], v[152:153], v[40:41]
	v_pk_fma_f32 v[154:155], v[58:59], v[154:155], v[42:43]
	v_pk_fma_f32 v[156:157], v[60:61], v[156:157], v[44:45]
	v_pk_fma_f32 v[158:159], v[62:63], v[158:159], v[46:47]
	v_cvt_pk_bf16_f32 v184, v144, v145
	v_cvt_pk_bf16_f32 v185, v146, v147
	v_cvt_pk_bf16_f32 v186, v148, v149
	v_cvt_pk_bf16_f32 v187, v150, v151
	v_cvt_pk_bf16_f32 v188, v152, v153
	v_cvt_pk_bf16_f32 v189, v154, v155
	v_cvt_pk_bf16_f32 v190, v156, v157
	v_cvt_pk_bf16_f32 v191, v158, v159
	s_add_i32 s10, s98, 0xd
	s_lshl_b32 s10, s10, 11
	s_add_u32 s28, s26, s10
	s_addc_u32 s29, s27, 0
	global_store_dwordx4 v2, v[184:187], s[28:29] sc1
	global_store_dwordx4 v2, v[188:191], s[28:29] offset:1024 sc1
	s_waitcnt vmcnt(12)
; __device__ __forceinline__ void norm_phase(const Params& P, unsigned char* ws, int layer, int which, int nrows, bool first, int lane, int wave, const float* pend_part, int pend_ns, const float* pend_gate) {
;     ...
;     for (int row = MLAT + gw; row < nrows; row += NGW) {
;         float* wrow = (float*)(ws + WS_Y) + (size_t)(row - MLAT) * DM;
;         const float* srow = first ? P.in[I_CTX] + (size_t)(row - MLAT) * DM : wrow;
;         const float* mod = (const float*)(ws + WS_MOD) + (size_t)(layer * 9 + 8) * 6144 + which * 3 * DM;
;         f32x4 v[4]; float ss = 0.f;
; #pragma unroll
;         for (int j = 0; j < 4; ++j) v[j] = *(const f32x4*)(srow + 4 * lane + 256 * j);
;         if (pend_ns > 0) {
; #pragma unroll
;             for (int j = 0; j < 4; ++j) { const int col = 4 * lane + 256 * j; f32x4 a = (f32x4){0.f, 0.f, 0.f, 0.f};
;                 for (int ks = 0; ks < pend_ns; ++ks) a = a + *(const f32x4*)(pend_part + ((size_t)ks * MCTX + (row - MLAT)) * DM + col);
;                 v[j] = v[j] + *(const f32x4*)(pend_gate + col) * a; }
;         }
; #pragma unroll
;     ...
; #pragma unroll
;         for (int r = 0; r < NR; ++r) { const int row = row0 + r * NGW;
;             const float rstd = rsqrtf(wave_sum(ss[r], lane) * (1.0f / DM) + EPS);
;             const float* mod = (const float*)(ws + WS_MOD) + (size_t)(layer * 9 + (row >> 12)) * 6144 + which * 3 * DM;
; #pragma unroll
;             for (int j = 0; j < 2; ++j) { const int col = 8 * lane + 512 * j; u32x4 hw, xw;
; #pragma unroll
;                 for (int q = 0; q < 2; ++q) {
;                     const f32x4 g4 = *(const f32x4*)(g + col + 4 * q), sh = *(const f32x4*)(mod + col + 4 * q), sc = *(const f32x4*)(mod + DM + col + 4 * q);
;                     const f32x4 h = (v[r][j][q] * rstd) * g4 * (sc + 1.0f) + sh;
;                     if (q == 0) { hw.x = cvt_pk_bf16(h[0], h[1]); hw.y = cvt_pk_bf16(h[2], h[3]); xw.x = cvt_pk_bf16(v[r][j][q][0], v[r][j][q][1]); xw.y = cvt_pk_bf16(v[r][j][q][2], v[r][j][q][3]); }
;                     else { hw.z = cvt_pk_bf16(h[0], h[1]); hw.w = cvt_pk_bf16(h[2], h[3]); xw.z = cvt_pk_bf16(v[r][j][q][0], v[r][j][q][1]); xw.w = cvt_pk_bf16(v[r][j][q][2], v[r][j][q][3]); }
;                 }
;                 *(u32x4*)(H + (size_t)row * DM + col) = hw;
;                 if (first) *(u32x4*)(XB + (size_t)row * DM + col) = xw;
;             } }
	v_lshlrev_b32_e32 v128, 16, v112
	v_and_b32_e32 v129, 0xffff0000, v112
	v_lshlrev_b32_e32 v130, 16, v113
	v_and_b32_e32 v131, 0xffff0000, v113
	v_lshlrev_b32_e32 v132, 16, v114
	v_and_b32_e32 v133, 0xffff0000, v114
	v_lshlrev_b32_e32 v134, 16, v115
	v_and_b32_e32 v135, 0xffff0000, v115
	v_lshlrev_b32_e32 v136, 16, v116
	v_and_b32_e32 v137, 0xffff0000, v116
	v_lshlrev_b32_e32 v138, 16, v117
	v_and_b32_e32 v139, 0xffff0000, v117
	v_lshlrev_b32_e32 v140, 16, v118
	v_and_b32_e32 v141, 0xffff0000, v118
	v_lshlrev_b32_e32 v142, 16, v119
	v_and_b32_e32 v143, 0xffff0000, v119
	v_lshlrev_b32_e32 v144, 16, v120
	v_and_b32_e32 v145, 0xffff0000, v120
	v_lshlrev_b32_e32 v146, 16, v121
	v_and_b32_e32 v147, 0xffff0000, v121
	v_lshlrev_b32_e32 v148, 16, v122
	v_and_b32_e32 v149, 0xffff0000, v122
	v_lshlrev_b32_e32 v150, 16, v123
	v_and_b32_e32 v151, 0xffff0000, v123
	v_lshlrev_b32_e32 v152, 16, v124
	v_and_b32_e32 v153, 0xffff0000, v124
	v_lshlrev_b32_e32 v154, 16, v125
	v_and_b32_e32 v155, 0xffff0000, v125
	v_lshlrev_b32_e32 v156, 16, v126
	v_and_b32_e32 v157, 0xffff0000, v126
	v_lshlrev_b32_e32 v158, 16, v127
	v_and_b32_e32 v159, 0xffff0000, v127
	v_pk_mul_f32 v[160:161], v[128:129], v[128:129]
	v_pk_mul_f32 v[162:163], v[144:145], v[144:145]
	v_pk_fma_f32 v[160:161], v[130:131], v[130:131], v[160:161]
	v_pk_fma_f32 v[162:163], v[146:147], v[146:147], v[162:163]
	v_pk_fma_f32 v[160:161], v[132:133], v[132:133], v[160:161]
	v_pk_fma_f32 v[162:163], v[148:149], v[148:149], v[162:163]
	v_pk_fma_f32 v[160:161], v[134:135], v[134:135], v[160:161]
	v_pk_fma_f32 v[162:163], v[150:151], v[150:151], v[162:163]
	v_pk_fma_f32 v[160:161], v[136:137], v[136:137], v[160:161]
	v_pk_fma_f32 v[162:163], v[152:153], v[152:153], v[162:163]
	v_pk_fma_f32 v[160:161], v[138:139], v[138:139], v[160:161]
	v_pk_fma_f32 v[162:163], v[154:155], v[154:155], v[162:163]
	v_pk_fma_f32 v[160:161], v[140:141], v[140:141], v[160:161]
	v_pk_fma_f32 v[162:163], v[156:157], v[156:157], v[162:163]
	v_pk_fma_f32 v[160:161], v[142:143], v[142:143], v[160:161]
	v_pk_fma_f32 v[162:163], v[158:159], v[158:159], v[162:163]
	v_add_f32_e32 v160, v160, v161
	v_add_f32_e32 v162, v162, v163
	ds_bpermute_b32 v164, v5, v160
	ds_bpermute_b32 v165, v5, v162
	s_waitcnt lgkmcnt(0)
	v_add_f32_e32 v160, v160, v164
	v_add_f32_e32 v162, v162, v165
	ds_bpermute_b32 v164, v6, v160
	ds_bpermute_b32 v165, v6, v162
	s_waitcnt lgkmcnt(0)
	v_add_f32_e32 v160, v160, v164
	v_add_f32_e32 v162, v162, v165
	ds_bpermute_b32 v164, v7, v160
	ds_bpermute_b32 v165, v7, v162
	s_waitcnt lgkmcnt(0)
	v_add_f32_e32 v160, v160, v164
	v_add_f32_e32 v162, v162, v165
	ds_bpermute_b32 v164, v9, v160
	ds_bpermute_b32 v165, v9, v162
	s_waitcnt lgkmcnt(0)
	v_add_f32_e32 v160, v160, v164
	v_add_f32_e32 v162, v162, v165
	ds_bpermute_b32 v164, v10, v160
	ds_bpermute_b32 v165, v10, v162
	s_waitcnt lgkmcnt(0)
	v_add_f32_e32 v160, v160, v164
	v_add_f32_e32 v162, v162, v165
	ds_bpermute_b32 v164, v11, v160
	ds_bpermute_b32 v165, v11, v162
	s_waitcnt lgkmcnt(0)
	v_add_f32_e32 v160, v160, v164
	v_add_f32_e32 v162, v162, v165
	v_fmamk_f32 v160, v160, 0x3a800000, v194
	v_fmamk_f32 v162, v162, 0x3a800000, v194
	v_rsq_f32_e32 v160, v160
	v_rsq_f32_e32 v162, v162
	s_nop 0
	v_pk_mul_f32 v[128:129], v[160:161], v[128:129] op_sel_hi:[0,1]
	v_pk_mul_f32 v[130:131], v[160:161], v[130:131] op_sel_hi:[0,1]
	v_pk_mul_f32 v[132:133], v[160:161], v[132:133] op_sel_hi:[0,1]
	v_pk_mul_f32 v[134:135], v[160:161], v[134:135] op_sel_hi:[0,1]
	v_pk_mul_f32 v[136:137], v[160:161], v[136:137] op_sel_hi:[0,1]
	v_pk_mul_f32 v[138:139], v[160:161], v[138:139] op_sel_hi:[0,1]
	v_pk_mul_f32 v[140:141], v[160:161], v[140:141] op_sel_hi:[0,1]
	v_pk_mul_f32 v[142:143], v[160:161], v[142:143] op_sel_hi:[0,1]
	v_pk_mul_f32 v[128:129], v[16:17], v[128:129]
	v_pk_mul_f32 v[130:131], v[18:19], v[130:131]
	v_pk_mul_f32 v[132:133], v[20:21], v[132:133]
	v_pk_mul_f32 v[134:135], v[22:23], v[134:135]
	v_pk_mul_f32 v[136:137], v[24:25], v[136:137]
	v_pk_mul_f32 v[138:139], v[26:27], v[138:139]
	v_pk_mul_f32 v[140:141], v[28:29], v[140:141]
	v_pk_mul_f32 v[142:143], v[30:31], v[142:143]
	v_pk_fma_f32 v[128:129], v[48:49], v[128:129], v[32:33]
	v_pk_fma_f32 v[130:131], v[50:51], v[130:131], v[34:35]
	v_pk_fma_f32 v[132:133], v[52:53], v[132:133], v[36:37]
	v_pk_fma_f32 v[134:135], v[54:55], v[134:135], v[38:39]
	v_pk_fma_f32 v[136:137], v[56:57], v[136:137], v[40:41]
	v_pk_fma_f32 v[138:139], v[58:59], v[138:139], v[42:43]
	v_pk_fma_f32 v[140:141], v[60:61], v[140:141], v[44:45]
	v_pk_fma_f32 v[142:143], v[62:63], v[142:143], v[46:47]
	v_cvt_pk_bf16_f32 v176, v128, v129
	v_cvt_pk_bf16_f32 v177, v130, v131
	v_cvt_pk_bf16_f32 v178, v132, v133
	v_cvt_pk_bf16_f32 v179, v134, v135
	v_cvt_pk_bf16_f32 v180, v136, v137
	v_cvt_pk_bf16_f32 v181, v138, v139
	v_cvt_pk_bf16_f32 v182, v140, v141
	v_cvt_pk_bf16_f32 v183, v142, v143
	s_add_i32 s10, s98, 0xe
	s_lshl_b32 s10, s10, 11
	s_add_u32 s28, s26, s10
	s_addc_u32 s29, s27, 0
	global_store_dwordx4 v2, v[176:179], s[28:29] sc1
	global_store_dwordx4 v2, v[180:183], s[28:29] offset:1024 sc1
	v_pk_mul_f32 v[144:145], v[162:163], v[144:145] op_sel_hi:[0,1]
	v_pk_mul_f32 v[146:147], v[162:163], v[146:147] op_sel_hi:[0,1]
	v_pk_mul_f32 v[148:149], v[162:163], v[148:149] op_sel_hi:[0,1]
	v_pk_mul_f32 v[150:151], v[162:163], v[150:151] op_sel_hi:[0,1]
	v_pk_mul_f32 v[152:153], v[162:163], v[152:153] op_sel_hi:[0,1]
	v_pk_mul_f32 v[154:155], v[162:163], v[154:155] op_sel_hi:[0,1]
	v_pk_mul_f32 v[156:157], v[162:163], v[156:157] op_sel_hi:[0,1]
	v_pk_mul_f32 v[158:159], v[162:163], v[158:159] op_sel_hi:[0,1]
	v_pk_mul_f32 v[144:145], v[16:17], v[144:145]
	v_pk_mul_f32 v[146:147], v[18:19], v[146:147]
	v_pk_mul_f32 v[148:149], v[20:21], v[148:149]
	v_pk_mul_f32 v[150:151], v[22:23], v[150:151]
	v_pk_mul_f32 v[152:153], v[24:25], v[152:153]
	v_pk_mul_f32 v[154:155], v[26:27], v[154:155]
	v_pk_mul_f32 v[156:157], v[28:29], v[156:157]
	v_pk_mul_f32 v[158:159], v[30:31], v[158:159]
	v_pk_fma_f32 v[144:145], v[48:49], v[144:145], v[32:33]
	v_pk_fma_f32 v[146:147], v[50:51], v[146:147], v[34:35]
	v_pk_fma_f32 v[148:149], v[52:53], v[148:149], v[36:37]
	v_pk_fma_f32 v[150:151], v[54:55], v[150:151], v[38:39]
	v_pk_fma_f32 v[152:153], v[56:57], v[152:153], v[40:41]
	v_pk_fma_f32 v[154:155], v[58:59], v[154:155], v[42:43]
	v_pk_fma_f32 v[156:157], v[60:61], v[156:157], v[44:45]
	v_pk_fma_f32 v[158:159], v[62:63], v[158:159], v[46:47]
	v_cvt_pk_bf16_f32 v184, v144, v145
	v_cvt_pk_bf16_f32 v185, v146, v147
	v_cvt_pk_bf16_f32 v186, v148, v149
	v_cvt_pk_bf16_f32 v187, v150, v151
	v_cvt_pk_bf16_f32 v188, v152, v153
	v_cvt_pk_bf16_f32 v189, v154, v155
	v_cvt_pk_bf16_f32 v190, v156, v157
	v_cvt_pk_bf16_f32 v191, v158, v159
	s_add_i32 s10, s98, 0xf
	s_lshl_b32 s10, s10, 11
	s_add_u32 s28, s26, s10
	s_addc_u32 s29, s27, 0
	global_store_dwordx4 v2, v[184:187], s[28:29] sc1
	global_store_dwordx4 v2, v[188:191], s[28:29] offset:1024 sc1
	s_nop 1
	s_cmp_eq_u32 s99, 0
	s_cbranch_scc1 .LBB0_909
	s_branch .LBB0_951
